# LN epilogue part3: gamma/beta preloaded once per unit, per-step vmcnt(0) drains removed
# speedup vs baseline: 1.0088x; 1.0088x over previous
; template <int EPI>
; DI void gemm_unit(const GemmP& g, int pm, int pn) {
;     ...
;     __syncthreads();
; #pragma unroll
;     for (int ai = 0; ai < 2; ++ai)
; #pragma unroll
;       for (int m = 0; m < 4; ++m) {
;         const int rl = ai * 128 + wr * 64 + m * 16 + fr;
;         const float mean = mr[rl * 2], rs = mr[rl * 2 + 1];
;         const int row = row0 + ai * 128 + m * 16;
; #pragma unroll
;         for (int bj = 0; bj < 2; ++bj)
; #pragma unroll
;           for (int n = 0; n < 2; ++n) {
;             const int col = colb + bj * 128 + n * 16;
;             const f32x4 gg = *(const f32x4*)(g.ln_g + col), bb = *(const f32x4*)(g.ln_b + col);
;             const f32x4 o = (acc[ai][bj][m][n] - mean) * rs * gg + bb;
;             const size_t idx = (size_t)row * 2048 + col;
;             if (g.outf) *(f32x4*)(g.outf + idx) = o;
;             uint2 ob; ob.x = pk2(o[0], o[1]); ob.y = pk2(o[2], o[3]);
;             *(uint2*)(g.outb + idx) = ob;
;           }
;       }
.LBB0_81:
	s_or_b64 exec, exec, s[6:7]
	v_lshlrev_b64 v[186:187], 2, v[132:133]
	v_lshl_add_u64 v[130:131], s[52:53], 0, v[186:187]
	v_lshl_add_u64 v[186:187], s[10:11], 0, v[186:187]
	global_load_dwordx4 v[224:227], v[130:131], off
	global_load_dwordx4 v[228:231], v[130:131], off offset:64
	global_load_dwordx4 v[232:235], v[130:131], off offset:512
	global_load_dwordx4 v[236:239], v[130:131], off offset:576
	global_load_dwordx4 v[240:243], v[186:187], off
	global_load_dwordx4 v[244:247], v[186:187], off offset:64
	global_load_dwordx4 v[248:251], v[186:187], off offset:512
	global_load_dwordx4 v[194:197], v[186:187], off offset:576
	s_waitcnt lgkmcnt(0)
	s_barrier
	s_waitcnt vmcnt(0)
	v_mov_b64_e32 v[2:3], v[224:225]
	v_mov_b64_e32 v[4:5], v[226:227]
	v_mov_b64_e32 v[190:191], v[240:241]
	v_mov_b64_e32 v[192:193], v[242:243]
	v_lshlrev_b32_e32 v0, 3, v0
	v_add_u32_e32 v0, 0, v0
	ds_read_b64 v[188:189], v0 offset:8192
	v_cndmask_b32_e64 v133, 0, 1, s[20:21]
	v_cmp_ne_u32_e64 s[6:7], 1, v133
	s_andn2_b64 vcc, exec, s[20:21]
	s_waitcnt lgkmcnt(0)
	v_sub_f32_e32 v129, v129, v188
	v_sub_f32_e32 v128, v128, v188
	v_sub_f32_e32 v127, v127, v188
	v_sub_f32_e32 v126, v126, v188
	v_pk_mul_f32 v[126:127], v[188:189], v[126:127] op_sel:[1,0]
	v_pk_mul_f32 v[128:129], v[188:189], v[128:129] op_sel:[1,0]
	v_pk_fma_f32 v[2:3], v[2:3], v[126:127], v[190:191]
	v_pk_fma_f32 v[4:5], v[4:5], v[128:129], v[192:193]
	v_lshl_add_u64 v[126:127], v[138:139], 2, s[88:89]
	s_cbranch_vccnz .LBB0_83
	global_store_dwordx4 v[126:127], v[2:5], off
.LBB0_83:
	s_nop 1
	v_cvt_pk_bf16_f32 v2, v2, v3
	v_cvt_pk_bf16_f32 v3, v4, v5
	global_store_dwordx2 v[136:137], v[2:3], off
	v_mov_b64_e32 v[2:3], v[228:229]
	v_mov_b64_e32 v[4:5], v[230:231]
	s_nop 0
	v_mov_b64_e32 v[136:137], v[244:245]
	v_mov_b64_e32 v[138:139], v[246:247]
	v_mov_b32_e32 v128, v189
	v_mov_b32_e32 v129, v189
	v_sub_f32_e32 v123, v123, v188
	v_sub_f32_e32 v122, v122, v188
	v_sub_f32_e32 v191, v125, v188
	v_sub_f32_e32 v190, v124, v188
	v_mov_b32_e32 v124, v189
	v_mov_b32_e32 v125, v189
	v_pk_mul_f32 v[190:191], v[124:125], v[190:191]
	v_pk_mul_f32 v[122:123], v[128:129], v[122:123]
	s_and_b64 vcc, exec, s[6:7]
	v_pk_fma_f32 v[2:3], v[122:123], v[2:3], v[136:137]
	v_pk_fma_f32 v[4:5], v[190:191], v[4:5], v[138:139]
	s_cbranch_vccnz .LBB0_85
	global_store_dwordx4 v[126:127], v[2:5], off offset:64
.LBB0_85:
	v_or_b32_e32 v122, 16, v132
	v_ashrrev_i32_e32 v123, 31, v122
	v_lshl_add_u64 v[136:137], v[134:135], 0, v[122:123]
	v_cvt_pk_bf16_f32 v2, v2, v3
	v_cvt_pk_bf16_f32 v3, v4, v5
	v_lshl_add_u64 v[4:5], v[136:137], 1, s[66:67]
	global_store_dwordx2 v[4:5], v[2:3], off
	v_mov_b64_e32 v[2:3], v[232:233]
	v_mov_b64_e32 v[4:5], v[234:235]
	s_nop 0
	v_mov_b64_e32 v[136:137], v[248:249]
	v_mov_b64_e32 v[138:139], v[250:251]
	v_sub_f32_e32 v119, v119, v188
	v_sub_f32_e32 v118, v118, v188
	v_sub_f32_e32 v121, v121, v188
	v_sub_f32_e32 v120, v120, v188
	v_pk_mul_f32 v[120:121], v[124:125], v[120:121]
	v_pk_mul_f32 v[118:119], v[128:129], v[118:119]
	s_and_b64 vcc, exec, s[6:7]
	v_pk_fma_f32 v[2:3], v[118:119], v[2:3], v[136:137]
	v_pk_fma_f32 v[4:5], v[120:121], v[4:5], v[138:139]
	s_cbranch_vccnz .LBB0_87
	global_store_dwordx4 v[126:127], v[2:5], off offset:512
.LBB0_87:
	v_or_b32_e32 v118, 0x80, v132
	v_ashrrev_i32_e32 v119, 31, v118
	v_lshl_add_u64 v[120:121], v[134:135], 0, v[118:119]
	v_cvt_pk_bf16_f32 v2, v2, v3
	v_cvt_pk_bf16_f32 v3, v4, v5
	v_lshl_add_u64 v[4:5], v[120:121], 1, s[66:67]
	global_store_dwordx2 v[4:5], v[2:3], off
	v_mov_b64_e32 v[2:3], v[236:237]
	v_mov_b64_e32 v[4:5], v[238:239]
	s_nop 0
	v_mov_b64_e32 v[136:137], v[194:195]
	v_mov_b64_e32 v[138:139], v[196:197]
	v_sub_f32_e32 v115, v115, v188
	v_sub_f32_e32 v114, v114, v188
	v_sub_f32_e32 v117, v117, v188
	v_sub_f32_e32 v116, v116, v188
	v_mov_b32_e32 v188, v189
	v_pk_mul_f32 v[116:117], v[188:189], v[116:117]
	v_pk_mul_f32 v[114:115], v[128:129], v[114:115]
	s_and_b64 vcc, exec, s[6:7]
	v_pk_fma_f32 v[2:3], v[114:115], v[2:3], v[136:137]
	v_pk_fma_f32 v[4:5], v[116:117], v[4:5], v[138:139]
	s_cbranch_vccnz .LBB0_89
	global_store_dwordx4 v[126:127], v[2:5], off offset:576
.LBB0_89:
	v_or_b32_e32 v114, 0x90, v132
	v_ashrrev_i32_e32 v115, 31, v114
	v_lshl_add_u64 v[116:117], v[134:135], 0, v[114:115]
	v_cvt_pk_bf16_f32 v2, v2, v3
	v_cvt_pk_bf16_f32 v3, v4, v5
	v_lshl_add_u64 v[4:5], v[116:117], 1, s[66:67]
	global_store_dwordx2 v[4:5], v[2:3], off
	v_mov_b64_e32 v[2:3], v[224:225]
	v_mov_b64_e32 v[4:5], v[226:227]
	s_nop 0
	v_mov_b64_e32 v[124:125], v[240:241]
	v_mov_b64_e32 v[126:127], v[242:243]
	ds_read_b64 v[116:117], v0 offset:8320
	s_and_b64 vcc, exec, s[6:7]
	s_waitcnt lgkmcnt(0)
	v_sub_f32_e32 v111, v111, v116
	v_sub_f32_e32 v110, v110, v116
	v_sub_f32_e32 v113, v113, v116
	v_sub_f32_e32 v112, v112, v116
	v_pk_mul_f32 v[112:113], v[116:117], v[112:113] op_sel:[1,0]
	v_pk_mul_f32 v[110:111], v[116:117], v[110:111] op_sel:[1,0]
	v_pk_fma_f32 v[4:5], v[4:5], v[112:113], v[126:127]
	v_pk_fma_f32 v[2:3], v[2:3], v[110:111], v[124:125]
	v_lshl_add_u64 v[110:111], v[144:145], 2, s[88:89]
	s_cbranch_vccnz .LBB0_91
	global_store_dwordx4 v[110:111], v[2:5], off
.LBB0_91:
	s_nop 1
	v_cvt_pk_bf16_f32 v2, v2, v3
	v_cvt_pk_bf16_f32 v3, v4, v5
	global_store_dwordx2 v[142:143], v[2:3], off
	v_mov_b64_e32 v[2:3], v[228:229]
	v_mov_b64_e32 v[4:5], v[230:231]
	s_nop 0
	v_mov_b64_e32 v[124:125], v[244:245]
	v_mov_b64_e32 v[126:127], v[246:247]
	v_mov_b32_e32 v112, v117
	v_mov_b32_e32 v113, v117
	v_sub_f32_e32 v121, v107, v116
	v_sub_f32_e32 v120, v106, v116
	v_sub_f32_e32 v109, v109, v116
	v_sub_f32_e32 v108, v108, v116
	v_mov_b32_e32 v106, v117
	v_mov_b32_e32 v107, v117
	v_pk_mul_f32 v[108:109], v[106:107], v[108:109]
	v_pk_mul_f32 v[120:121], v[112:113], v[120:121]
	s_and_b64 vcc, exec, s[6:7]
	v_pk_fma_f32 v[2:3], v[120:121], v[2:3], v[124:125]
	v_pk_fma_f32 v[4:5], v[108:109], v[4:5], v[126:127]
	s_cbranch_vccnz .LBB0_93
	global_store_dwordx4 v[110:111], v[2:5], off offset:64
; template <int EPI>
; DI void gemm_unit(const GemmP& g, int pm, int pn) {
;     ...
; #pragma unroll
;     for (int ai = 0; ai < 2; ++ai)
; #pragma unroll
;       for (int m = 0; m < 4; ++m) {
;         const int rl = ai * 128 + wr * 64 + m * 16 + fr;
;         const float mean = mr[rl * 2], rs = mr[rl * 2 + 1];
;         const int row = row0 + ai * 128 + m * 16;
; #pragma unroll
;         for (int bj = 0; bj < 2; ++bj)
; #pragma unroll
;           for (int n = 0; n < 2; ++n) {
;             const int col = colb + bj * 128 + n * 16;
;             const f32x4 gg = *(const f32x4*)(g.ln_g + col), bb = *(const f32x4*)(g.ln_b + col);
;             const f32x4 o = (acc[ai][bj][m][n] - mean) * rs * gg + bb;
;             const size_t idx = (size_t)row * 2048 + col;
;             if (g.outf) *(f32x4*)(g.outf + idx) = o;
;             uint2 ob; ob.x = pk2(o[0], o[1]); ob.y = pk2(o[2], o[3]);
;             *(uint2*)(g.outb + idx) = ob;
;           }
;       }
.LBB0_93:
	v_lshl_add_u64 v[108:109], v[140:141], 0, v[122:123]
	s_nop 0
	v_cvt_pk_bf16_f32 v2, v2, v3
	v_cvt_pk_bf16_f32 v3, v4, v5
	v_lshl_add_u64 v[4:5], v[108:109], 1, s[66:67]
	global_store_dwordx2 v[4:5], v[2:3], off
	v_mov_b64_e32 v[2:3], v[232:233]
	v_mov_b64_e32 v[4:5], v[234:235]
	s_nop 0
	v_mov_b64_e32 v[124:125], v[248:249]
	v_mov_b64_e32 v[126:127], v[250:251]
	v_sub_f32_e32 v103, v103, v116
	v_sub_f32_e32 v102, v102, v116
	v_sub_f32_e32 v105, v105, v116
	v_sub_f32_e32 v104, v104, v116
	v_pk_mul_f32 v[104:105], v[106:107], v[104:105]
	v_pk_mul_f32 v[102:103], v[112:113], v[102:103]
	s_and_b64 vcc, exec, s[6:7]
	v_pk_fma_f32 v[2:3], v[102:103], v[2:3], v[124:125]
	v_pk_fma_f32 v[4:5], v[104:105], v[4:5], v[126:127]
	s_cbranch_vccnz .LBB0_95
	global_store_dwordx4 v[110:111], v[2:5], off offset:512
.LBB0_95:
	v_lshl_add_u64 v[102:103], v[140:141], 0, v[118:119]
	s_nop 0
	v_cvt_pk_bf16_f32 v2, v2, v3
	v_cvt_pk_bf16_f32 v3, v4, v5
	v_lshl_add_u64 v[4:5], v[102:103], 1, s[66:67]
	global_store_dwordx2 v[4:5], v[2:3], off
	v_mov_b64_e32 v[2:3], v[236:237]
	v_mov_b64_e32 v[4:5], v[238:239]
	s_nop 0
	v_mov_b64_e32 v[102:103], v[194:195]
	v_mov_b64_e32 v[104:105], v[196:197]
	v_sub_f32_e32 v99, v99, v116
	v_sub_f32_e32 v98, v98, v116
	v_sub_f32_e32 v101, v101, v116
	v_sub_f32_e32 v100, v100, v116
	v_mov_b32_e32 v116, v117
	v_pk_mul_f32 v[100:101], v[116:117], v[100:101]
	v_pk_mul_f32 v[98:99], v[112:113], v[98:99]
	s_and_b64 vcc, exec, s[6:7]
	v_pk_fma_f32 v[2:3], v[98:99], v[2:3], v[102:103]
	v_pk_fma_f32 v[4:5], v[100:101], v[4:5], v[104:105]
	s_cbranch_vccnz .LBB0_97
	global_store_dwordx4 v[110:111], v[2:5], off offset:576
.LBB0_97:
	v_lshl_add_u64 v[98:99], v[140:141], 0, v[114:115]
	s_nop 0
	v_cvt_pk_bf16_f32 v2, v2, v3
	v_cvt_pk_bf16_f32 v3, v4, v5
	v_lshl_add_u64 v[4:5], v[98:99], 1, s[66:67]
	global_store_dwordx2 v[4:5], v[2:3], off
	v_mov_b64_e32 v[2:3], v[224:225]
	v_mov_b64_e32 v[4:5], v[226:227]
	s_nop 0
	v_mov_b64_e32 v[100:101], v[240:241]
	v_mov_b64_e32 v[102:103], v[242:243]
	ds_read_b64 v[98:99], v0 offset:8448
	s_and_b64 vcc, exec, s[6:7]
	s_waitcnt lgkmcnt(0)
	v_sub_f32_e32 v95, v95, v98
	v_sub_f32_e32 v94, v94, v98
	v_sub_f32_e32 v97, v97, v98
	v_sub_f32_e32 v96, v96, v98
	v_pk_mul_f32 v[96:97], v[98:99], v[96:97] op_sel:[1,0]
	v_pk_mul_f32 v[94:95], v[98:99], v[94:95] op_sel:[1,0]
	v_pk_fma_f32 v[4:5], v[4:5], v[96:97], v[102:103]
	v_pk_fma_f32 v[2:3], v[2:3], v[94:95], v[100:101]
	v_lshl_add_u64 v[94:95], v[150:151], 2, s[88:89]
	s_cbranch_vccnz .LBB0_99
	global_store_dwordx4 v[94:95], v[2:5], off
.LBB0_99:
	s_nop 1
	v_cvt_pk_bf16_f32 v2, v2, v3
	v_cvt_pk_bf16_f32 v3, v4, v5
	global_store_dwordx2 v[148:149], v[2:3], off
	v_mov_b64_e32 v[2:3], v[228:229]
	v_mov_b64_e32 v[4:5], v[230:231]
	s_nop 0
	v_mov_b64_e32 v[100:101], v[244:245]
	v_mov_b64_e32 v[102:103], v[246:247]
	v_mov_b32_e32 v96, v99
	v_mov_b32_e32 v97, v99
	v_sub_f32_e32 v105, v91, v98
	v_sub_f32_e32 v104, v90, v98
	v_sub_f32_e32 v93, v93, v98
	v_sub_f32_e32 v92, v92, v98
	v_mov_b32_e32 v90, v99
	v_mov_b32_e32 v91, v99
	v_pk_mul_f32 v[92:93], v[90:91], v[92:93]
	v_pk_mul_f32 v[104:105], v[96:97], v[104:105]
	s_and_b64 vcc, exec, s[6:7]
	v_pk_fma_f32 v[2:3], v[104:105], v[2:3], v[100:101]
	v_pk_fma_f32 v[4:5], v[92:93], v[4:5], v[102:103]
	s_cbranch_vccnz .LBB0_101
	global_store_dwordx4 v[94:95], v[2:5], off offset:64
.LBB0_101:
	v_lshl_add_u64 v[92:93], v[146:147], 0, v[122:123]
	s_nop 0
	v_cvt_pk_bf16_f32 v2, v2, v3
	v_cvt_pk_bf16_f32 v3, v4, v5
	v_lshl_add_u64 v[4:5], v[92:93], 1, s[66:67]
	global_store_dwordx2 v[4:5], v[2:3], off
	v_mov_b64_e32 v[2:3], v[232:233]
	v_mov_b64_e32 v[4:5], v[234:235]
	s_nop 0
	v_mov_b64_e32 v[100:101], v[248:249]
	v_mov_b64_e32 v[102:103], v[250:251]
	v_sub_f32_e32 v87, v87, v98
	v_sub_f32_e32 v86, v86, v98
	v_sub_f32_e32 v89, v89, v98
	v_sub_f32_e32 v88, v88, v98
	v_pk_mul_f32 v[88:89], v[90:91], v[88:89]
	v_pk_mul_f32 v[86:87], v[96:97], v[86:87]
	s_and_b64 vcc, exec, s[6:7]
	v_pk_fma_f32 v[2:3], v[86:87], v[2:3], v[100:101]
	v_pk_fma_f32 v[4:5], v[88:89], v[4:5], v[102:103]
	s_cbranch_vccnz .LBB0_103
	global_store_dwordx4 v[94:95], v[2:5], off offset:512
.LBB0_103:
	v_lshl_add_u64 v[86:87], v[146:147], 0, v[118:119]
	s_nop 0
	v_cvt_pk_bf16_f32 v2, v2, v3
	v_cvt_pk_bf16_f32 v3, v4, v5
	v_lshl_add_u64 v[4:5], v[86:87], 1, s[66:67]
	global_store_dwordx2 v[4:5], v[2:3], off
	v_mov_b64_e32 v[2:3], v[236:237]
	v_mov_b64_e32 v[4:5], v[238:239]
	s_nop 0
	v_mov_b64_e32 v[86:87], v[194:195]
	v_mov_b64_e32 v[88:89], v[196:197]
	v_sub_f32_e32 v83, v83, v98
	v_sub_f32_e32 v82, v82, v98
	v_sub_f32_e32 v85, v85, v98
	v_sub_f32_e32 v84, v84, v98
	v_mov_b32_e32 v98, v99
	v_pk_mul_f32 v[84:85], v[98:99], v[84:85]
	v_pk_mul_f32 v[82:83], v[96:97], v[82:83]
	s_and_b64 vcc, exec, s[6:7]
	v_pk_fma_f32 v[2:3], v[82:83], v[2:3], v[86:87]
	v_pk_fma_f32 v[4:5], v[84:85], v[4:5], v[88:89]
	s_cbranch_vccnz .LBB0_105
	global_store_dwordx4 v[94:95], v[2:5], off offset:576
.LBB0_105:
	v_lshl_add_u64 v[82:83], v[146:147], 0, v[114:115]
	s_nop 0
	v_cvt_pk_bf16_f32 v2, v2, v3
	v_cvt_pk_bf16_f32 v3, v4, v5
	v_lshl_add_u64 v[4:5], v[82:83], 1, s[66:67]
	global_store_dwordx2 v[4:5], v[2:3], off
	v_mov_b64_e32 v[2:3], v[224:225]
	v_mov_b64_e32 v[4:5], v[226:227]
	s_nop 0
	v_mov_b64_e32 v[84:85], v[240:241]
	v_mov_b64_e32 v[86:87], v[242:243]
	ds_read_b64 v[82:83], v0 offset:8576
	s_and_b64 vcc, exec, s[6:7]
	s_waitcnt lgkmcnt(0)
	v_sub_f32_e32 v79, v79, v82
	v_sub_f32_e32 v78, v78, v82
	v_sub_f32_e32 v81, v81, v82
	v_sub_f32_e32 v80, v80, v82
	v_pk_mul_f32 v[80:81], v[82:83], v[80:81] op_sel:[1,0]
	v_pk_mul_f32 v[78:79], v[82:83], v[78:79] op_sel:[1,0]
	v_pk_fma_f32 v[4:5], v[4:5], v[80:81], v[86:87]
	v_pk_fma_f32 v[2:3], v[2:3], v[78:79], v[84:85]
	v_lshl_add_u64 v[78:79], v[156:157], 2, s[88:89]
	s_cbranch_vccnz .LBB0_107
	global_store_dwordx4 v[78:79], v[2:5], off
; template <int EPI>
; DI void gemm_unit(const GemmP& g, int pm, int pn) {
;     ...
; #pragma unroll
;     for (int ai = 0; ai < 2; ++ai)
; #pragma unroll
;       for (int m = 0; m < 4; ++m) {
;         const int rl = ai * 128 + wr * 64 + m * 16 + fr;
;         const float mean = mr[rl * 2], rs = mr[rl * 2 + 1];
;         const int row = row0 + ai * 128 + m * 16;
; #pragma unroll
;         for (int bj = 0; bj < 2; ++bj)
; #pragma unroll
;           for (int n = 0; n < 2; ++n) {
;             const int col = colb + bj * 128 + n * 16;
;             const f32x4 gg = *(const f32x4*)(g.ln_g + col), bb = *(const f32x4*)(g.ln_b + col);
;             const f32x4 o = (acc[ai][bj][m][n] - mean) * rs * gg + bb;
;             const size_t idx = (size_t)row * 2048 + col;
;             if (g.outf) *(f32x4*)(g.outf + idx) = o;
;             uint2 ob; ob.x = pk2(o[0], o[1]); ob.y = pk2(o[2], o[3]);
;             *(uint2*)(g.outb + idx) = ob;
;           }
;       }
.LBB0_107:
	s_nop 1
	v_cvt_pk_bf16_f32 v2, v2, v3
	v_cvt_pk_bf16_f32 v3, v4, v5
	global_store_dwordx2 v[154:155], v[2:3], off
	v_mov_b64_e32 v[2:3], v[228:229]
	v_mov_b64_e32 v[4:5], v[230:231]
	s_nop 0
	v_mov_b64_e32 v[84:85], v[244:245]
	v_mov_b64_e32 v[86:87], v[246:247]
	v_mov_b32_e32 v80, v83
	v_mov_b32_e32 v81, v83
	v_sub_f32_e32 v89, v75, v82
	v_sub_f32_e32 v88, v74, v82
	v_sub_f32_e32 v77, v77, v82
	v_sub_f32_e32 v76, v76, v82
	v_mov_b32_e32 v74, v83
	v_mov_b32_e32 v75, v83
	v_pk_mul_f32 v[76:77], v[74:75], v[76:77]
	v_pk_mul_f32 v[88:89], v[80:81], v[88:89]
	s_and_b64 vcc, exec, s[6:7]
	v_pk_fma_f32 v[2:3], v[88:89], v[2:3], v[84:85]
	v_pk_fma_f32 v[4:5], v[76:77], v[4:5], v[86:87]
	s_cbranch_vccnz .LBB0_109
	global_store_dwordx4 v[78:79], v[2:5], off offset:64
.LBB0_109:
	v_lshl_add_u64 v[76:77], v[152:153], 0, v[122:123]
	s_nop 0
	v_cvt_pk_bf16_f32 v2, v2, v3
	v_cvt_pk_bf16_f32 v3, v4, v5
	v_lshl_add_u64 v[4:5], v[76:77], 1, s[66:67]
	global_store_dwordx2 v[4:5], v[2:3], off
	v_mov_b64_e32 v[2:3], v[232:233]
	v_mov_b64_e32 v[4:5], v[234:235]
	s_nop 0
	v_mov_b64_e32 v[84:85], v[248:249]
	v_mov_b64_e32 v[86:87], v[250:251]
	v_sub_f32_e32 v71, v71, v82
	v_sub_f32_e32 v70, v70, v82
	v_sub_f32_e32 v73, v73, v82
	v_sub_f32_e32 v72, v72, v82
	v_pk_mul_f32 v[72:73], v[74:75], v[72:73]
	v_pk_mul_f32 v[70:71], v[80:81], v[70:71]
	s_and_b64 vcc, exec, s[6:7]
	v_pk_fma_f32 v[2:3], v[70:71], v[2:3], v[84:85]
	v_pk_fma_f32 v[4:5], v[72:73], v[4:5], v[86:87]
	s_cbranch_vccnz .LBB0_111
	global_store_dwordx4 v[78:79], v[2:5], off offset:512
.LBB0_111:
	v_lshl_add_u64 v[70:71], v[152:153], 0, v[118:119]
	s_nop 0
	v_cvt_pk_bf16_f32 v2, v2, v3
	v_cvt_pk_bf16_f32 v3, v4, v5
	v_lshl_add_u64 v[4:5], v[70:71], 1, s[66:67]
	global_store_dwordx2 v[4:5], v[2:3], off
	v_mov_b64_e32 v[2:3], v[236:237]
	v_mov_b64_e32 v[4:5], v[238:239]
	s_nop 0
	v_mov_b64_e32 v[70:71], v[194:195]
	v_mov_b64_e32 v[72:73], v[196:197]
	v_sub_f32_e32 v67, v67, v82
	v_sub_f32_e32 v66, v66, v82
	v_sub_f32_e32 v69, v69, v82
	v_sub_f32_e32 v68, v68, v82
	v_mov_b32_e32 v82, v83
	v_pk_mul_f32 v[68:69], v[82:83], v[68:69]
	v_pk_mul_f32 v[66:67], v[80:81], v[66:67]
	s_and_b64 vcc, exec, s[6:7]
	v_pk_fma_f32 v[2:3], v[66:67], v[2:3], v[70:71]
	v_pk_fma_f32 v[4:5], v[68:69], v[4:5], v[72:73]
	s_cbranch_vccnz .LBB0_113
	global_store_dwordx4 v[78:79], v[2:5], off offset:576
.LBB0_113:
	v_lshl_add_u64 v[66:67], v[152:153], 0, v[114:115]
	s_nop 0
	v_cvt_pk_bf16_f32 v2, v2, v3
	v_cvt_pk_bf16_f32 v3, v4, v5
	v_lshl_add_u64 v[4:5], v[66:67], 1, s[66:67]
	global_store_dwordx2 v[4:5], v[2:3], off
	v_mov_b64_e32 v[2:3], v[224:225]
	v_mov_b64_e32 v[4:5], v[226:227]
	s_nop 0
	v_mov_b64_e32 v[68:69], v[240:241]
	v_mov_b64_e32 v[70:71], v[242:243]
	v_lshl_add_u32 v66, v206, 3, 0
	ds_read_b64 v[66:67], v66 offset:8192
	s_and_b64 vcc, exec, s[6:7]
	s_waitcnt lgkmcnt(0)
	v_sub_f32_e32 v63, v63, v66
	v_sub_f32_e32 v62, v62, v66
	v_sub_f32_e32 v65, v65, v66
	v_sub_f32_e32 v64, v64, v66
	v_pk_mul_f32 v[64:65], v[66:67], v[64:65] op_sel:[1,0]
	v_pk_mul_f32 v[62:63], v[66:67], v[62:63] op_sel:[1,0]
	v_pk_fma_f32 v[4:5], v[4:5], v[64:65], v[70:71]
	v_pk_fma_f32 v[2:3], v[2:3], v[62:63], v[68:69]
	v_lshl_add_u64 v[62:63], v[164:165], 2, s[88:89]
	s_cbranch_vccnz .LBB0_115
	global_store_dwordx4 v[62:63], v[2:5], off
.LBB0_115:
	s_nop 1
	v_cvt_pk_bf16_f32 v2, v2, v3
	v_cvt_pk_bf16_f32 v3, v4, v5
	global_store_dwordx2 v[162:163], v[2:3], off
	v_mov_b64_e32 v[2:3], v[228:229]
	v_mov_b64_e32 v[4:5], v[230:231]
	s_nop 0
	v_mov_b64_e32 v[68:69], v[244:245]
	v_mov_b64_e32 v[70:71], v[246:247]
	v_mov_b32_e32 v64, v67
	v_mov_b32_e32 v65, v67
	v_sub_f32_e32 v73, v59, v66
	v_sub_f32_e32 v72, v58, v66
	v_sub_f32_e32 v61, v61, v66
	v_sub_f32_e32 v60, v60, v66
	v_mov_b32_e32 v58, v67
	v_mov_b32_e32 v59, v67
	v_pk_mul_f32 v[60:61], v[58:59], v[60:61]
	v_pk_mul_f32 v[72:73], v[64:65], v[72:73]
	s_and_b64 vcc, exec, s[6:7]
	v_pk_fma_f32 v[2:3], v[72:73], v[2:3], v[68:69]
	v_pk_fma_f32 v[4:5], v[60:61], v[4:5], v[70:71]
	s_cbranch_vccnz .LBB0_117
	global_store_dwordx4 v[62:63], v[2:5], off offset:64
.LBB0_117:
	v_lshl_add_u64 v[60:61], v[158:159], 0, v[122:123]
	s_nop 0
	v_cvt_pk_bf16_f32 v2, v2, v3
	v_cvt_pk_bf16_f32 v3, v4, v5
	v_lshl_add_u64 v[4:5], v[60:61], 1, s[66:67]
	global_store_dwordx2 v[4:5], v[2:3], off
	v_mov_b64_e32 v[2:3], v[232:233]
	v_mov_b64_e32 v[4:5], v[234:235]
	s_nop 0
	v_mov_b64_e32 v[68:69], v[248:249]
	v_mov_b64_e32 v[70:71], v[250:251]
	v_sub_f32_e32 v55, v55, v66
	v_sub_f32_e32 v54, v54, v66
	v_sub_f32_e32 v57, v57, v66
	v_sub_f32_e32 v56, v56, v66
	v_pk_mul_f32 v[56:57], v[58:59], v[56:57]
	v_pk_mul_f32 v[54:55], v[64:65], v[54:55]
	s_and_b64 vcc, exec, s[6:7]
	v_pk_fma_f32 v[2:3], v[54:55], v[2:3], v[68:69]
	v_pk_fma_f32 v[4:5], v[56:57], v[4:5], v[70:71]
	s_cbranch_vccnz .LBB0_119
	global_store_dwordx4 v[62:63], v[2:5], off offset:512
.LBB0_119:
	v_lshl_add_u64 v[54:55], v[158:159], 0, v[118:119]
	s_nop 0
	v_cvt_pk_bf16_f32 v2, v2, v3
	v_cvt_pk_bf16_f32 v3, v4, v5
	v_lshl_add_u64 v[4:5], v[54:55], 1, s[66:67]
	global_store_dwordx2 v[4:5], v[2:3], off
	v_mov_b64_e32 v[2:3], v[236:237]
	v_mov_b64_e32 v[4:5], v[238:239]
	s_nop 0
	v_mov_b64_e32 v[54:55], v[194:195]
	v_mov_b64_e32 v[56:57], v[196:197]
	v_sub_f32_e32 v51, v51, v66
	v_sub_f32_e32 v50, v50, v66
	v_sub_f32_e32 v53, v53, v66
	v_sub_f32_e32 v52, v52, v66
	v_mov_b32_e32 v66, v67
	v_pk_mul_f32 v[52:53], v[66:67], v[52:53]
	v_pk_mul_f32 v[50:51], v[64:65], v[50:51]
	s_and_b64 vcc, exec, s[6:7]
	v_pk_fma_f32 v[2:3], v[50:51], v[2:3], v[54:55]
	v_pk_fma_f32 v[4:5], v[52:53], v[4:5], v[56:57]
	s_cbranch_vccnz .LBB0_121
	global_store_dwordx4 v[62:63], v[2:5], off offset:576
; template <int EPI>
; DI void gemm_unit(const GemmP& g, int pm, int pn) {
;     ...
; #pragma unroll
;     for (int ai = 0; ai < 2; ++ai)
; #pragma unroll
;       for (int m = 0; m < 4; ++m) {
;         const int rl = ai * 128 + wr * 64 + m * 16 + fr;
;         const float mean = mr[rl * 2], rs = mr[rl * 2 + 1];
;         const int row = row0 + ai * 128 + m * 16;
; #pragma unroll
;         for (int bj = 0; bj < 2; ++bj)
; #pragma unroll
;           for (int n = 0; n < 2; ++n) {
;             const int col = colb + bj * 128 + n * 16;
;             const f32x4 gg = *(const f32x4*)(g.ln_g + col), bb = *(const f32x4*)(g.ln_b + col);
;             const f32x4 o = (acc[ai][bj][m][n] - mean) * rs * gg + bb;
;             const size_t idx = (size_t)row * 2048 + col;
;             if (g.outf) *(f32x4*)(g.outf + idx) = o;
;             uint2 ob; ob.x = pk2(o[0], o[1]); ob.y = pk2(o[2], o[3]);
;             *(uint2*)(g.outb + idx) = ob;
;           }
;       }
.LBB0_121:
	v_lshl_add_u64 v[50:51], v[158:159], 0, v[114:115]
	s_nop 0
	v_cvt_pk_bf16_f32 v2, v2, v3
	v_cvt_pk_bf16_f32 v3, v4, v5
	v_lshl_add_u64 v[4:5], v[50:51], 1, s[66:67]
	global_store_dwordx2 v[4:5], v[2:3], off
	v_mov_b64_e32 v[2:3], v[224:225]
	v_mov_b64_e32 v[4:5], v[226:227]
	s_nop 0
	v_mov_b64_e32 v[52:53], v[240:241]
	v_mov_b64_e32 v[54:55], v[242:243]
	ds_read_b64 v[50:51], v0 offset:9344
	s_and_b64 vcc, exec, s[6:7]
	s_waitcnt lgkmcnt(0)
	v_sub_f32_e32 v47, v47, v50
	v_sub_f32_e32 v46, v46, v50
	v_sub_f32_e32 v49, v49, v50
	v_sub_f32_e32 v48, v48, v50
	v_pk_mul_f32 v[48:49], v[50:51], v[48:49] op_sel:[1,0]
	v_pk_mul_f32 v[46:47], v[50:51], v[46:47] op_sel:[1,0]
	v_pk_fma_f32 v[4:5], v[4:5], v[48:49], v[54:55]
	v_pk_fma_f32 v[2:3], v[2:3], v[46:47], v[52:53]
	v_lshl_add_u64 v[46:47], v[170:171], 2, s[88:89]
	s_cbranch_vccnz .LBB0_123
	global_store_dwordx4 v[46:47], v[2:5], off
.LBB0_123:
	s_nop 1
	v_cvt_pk_bf16_f32 v2, v2, v3
	v_cvt_pk_bf16_f32 v3, v4, v5
	global_store_dwordx2 v[168:169], v[2:3], off
	v_mov_b64_e32 v[2:3], v[228:229]
	v_mov_b64_e32 v[4:5], v[230:231]
	s_nop 0
	v_mov_b64_e32 v[52:53], v[244:245]
	v_mov_b64_e32 v[54:55], v[246:247]
	v_mov_b32_e32 v48, v51
	v_mov_b32_e32 v49, v51
	v_sub_f32_e32 v57, v43, v50
	v_sub_f32_e32 v56, v42, v50
	v_sub_f32_e32 v45, v45, v50
	v_sub_f32_e32 v44, v44, v50
	v_mov_b32_e32 v42, v51
	v_mov_b32_e32 v43, v51
	v_pk_mul_f32 v[44:45], v[42:43], v[44:45]
	v_pk_mul_f32 v[56:57], v[48:49], v[56:57]
	s_and_b64 vcc, exec, s[6:7]
	v_pk_fma_f32 v[2:3], v[56:57], v[2:3], v[52:53]
	v_pk_fma_f32 v[4:5], v[44:45], v[4:5], v[54:55]
	s_cbranch_vccnz .LBB0_125
	global_store_dwordx4 v[46:47], v[2:5], off offset:64
.LBB0_125:
	v_lshl_add_u64 v[44:45], v[166:167], 0, v[122:123]
	s_nop 0
	v_cvt_pk_bf16_f32 v2, v2, v3
	v_cvt_pk_bf16_f32 v3, v4, v5
	v_lshl_add_u64 v[4:5], v[44:45], 1, s[66:67]
	global_store_dwordx2 v[4:5], v[2:3], off
	v_mov_b64_e32 v[2:3], v[232:233]
	v_mov_b64_e32 v[4:5], v[234:235]
	s_nop 0
	v_mov_b64_e32 v[52:53], v[248:249]
	v_mov_b64_e32 v[54:55], v[250:251]
	v_sub_f32_e32 v39, v39, v50
	v_sub_f32_e32 v38, v38, v50
	v_sub_f32_e32 v41, v41, v50
	v_sub_f32_e32 v40, v40, v50
	v_pk_mul_f32 v[40:41], v[42:43], v[40:41]
	v_pk_mul_f32 v[38:39], v[48:49], v[38:39]
	s_and_b64 vcc, exec, s[6:7]
	v_pk_fma_f32 v[2:3], v[38:39], v[2:3], v[52:53]
	v_pk_fma_f32 v[4:5], v[40:41], v[4:5], v[54:55]
	s_cbranch_vccnz .LBB0_127
	global_store_dwordx4 v[46:47], v[2:5], off offset:512
.LBB0_127:
	v_lshl_add_u64 v[38:39], v[166:167], 0, v[118:119]
	s_nop 0
	v_cvt_pk_bf16_f32 v2, v2, v3
	v_cvt_pk_bf16_f32 v3, v4, v5
	v_lshl_add_u64 v[4:5], v[38:39], 1, s[66:67]
	global_store_dwordx2 v[4:5], v[2:3], off
	v_mov_b64_e32 v[2:3], v[236:237]
	v_mov_b64_e32 v[4:5], v[238:239]
	s_nop 0
	v_mov_b64_e32 v[38:39], v[194:195]
	v_mov_b64_e32 v[40:41], v[196:197]
	v_sub_f32_e32 v35, v35, v50
	v_sub_f32_e32 v34, v34, v50
	v_sub_f32_e32 v37, v37, v50
	v_sub_f32_e32 v36, v36, v50
	v_mov_b32_e32 v50, v51
	v_pk_mul_f32 v[36:37], v[50:51], v[36:37]
	v_pk_mul_f32 v[34:35], v[48:49], v[34:35]
	s_and_b64 vcc, exec, s[6:7]
	v_pk_fma_f32 v[2:3], v[34:35], v[2:3], v[38:39]
	v_pk_fma_f32 v[4:5], v[36:37], v[4:5], v[40:41]
	s_cbranch_vccnz .LBB0_129
	global_store_dwordx4 v[46:47], v[2:5], off offset:576
.LBB0_129:
	v_lshl_add_u64 v[34:35], v[166:167], 0, v[114:115]
	s_nop 0
	v_cvt_pk_bf16_f32 v2, v2, v3
	v_cvt_pk_bf16_f32 v3, v4, v5
	v_lshl_add_u64 v[4:5], v[34:35], 1, s[66:67]
	global_store_dwordx2 v[4:5], v[2:3], off
	v_mov_b64_e32 v[2:3], v[224:225]
	v_mov_b64_e32 v[4:5], v[226:227]
	s_nop 0
	v_mov_b64_e32 v[36:37], v[240:241]
	v_mov_b64_e32 v[38:39], v[242:243]
	ds_read_b64 v[34:35], v0 offset:9472
	s_and_b64 vcc, exec, s[6:7]
	s_waitcnt lgkmcnt(0)
	v_sub_f32_e32 v31, v31, v34
	v_sub_f32_e32 v30, v30, v34
	v_sub_f32_e32 v33, v33, v34
	v_sub_f32_e32 v32, v32, v34
	v_pk_mul_f32 v[32:33], v[34:35], v[32:33] op_sel:[1,0]
	v_pk_mul_f32 v[30:31], v[34:35], v[30:31] op_sel:[1,0]
	v_pk_fma_f32 v[4:5], v[4:5], v[32:33], v[38:39]
	v_pk_fma_f32 v[2:3], v[2:3], v[30:31], v[36:37]
	v_lshl_add_u64 v[30:31], v[174:175], 2, s[88:89]
	s_cbranch_vccnz .LBB0_131
	global_store_dwordx4 v[30:31], v[2:5], off
.LBB0_131:
	s_nop 1
	v_cvt_pk_bf16_f32 v2, v2, v3
	v_cvt_pk_bf16_f32 v3, v4, v5
	global_store_dwordx2 v[172:173], v[2:3], off
	v_mov_b64_e32 v[2:3], v[228:229]
	v_mov_b64_e32 v[4:5], v[230:231]
	s_nop 0
	v_mov_b64_e32 v[36:37], v[244:245]
	v_mov_b64_e32 v[38:39], v[246:247]
	v_mov_b32_e32 v32, v35
	v_mov_b32_e32 v33, v35
	v_sub_f32_e32 v41, v27, v34
	v_sub_f32_e32 v40, v26, v34
	v_sub_f32_e32 v29, v29, v34
	v_sub_f32_e32 v28, v28, v34
	v_mov_b32_e32 v26, v35
	v_mov_b32_e32 v27, v35
	v_pk_mul_f32 v[28:29], v[26:27], v[28:29]
	v_pk_mul_f32 v[40:41], v[32:33], v[40:41]
	s_and_b64 vcc, exec, s[6:7]
	v_pk_fma_f32 v[2:3], v[40:41], v[2:3], v[36:37]
	v_pk_fma_f32 v[4:5], v[28:29], v[4:5], v[38:39]
	s_cbranch_vccnz .LBB0_133
	global_store_dwordx4 v[30:31], v[2:5], off offset:64
; template <int EPI>
; DI void gemm_unit(const GemmP& g, int pm, int pn) {
;     ...
; #pragma unroll
;     for (int ai = 0; ai < 2; ++ai)
; #pragma unroll
;       for (int m = 0; m < 4; ++m) {
;         const int rl = ai * 128 + wr * 64 + m * 16 + fr;
;         const float mean = mr[rl * 2], rs = mr[rl * 2 + 1];
;         const int row = row0 + ai * 128 + m * 16;
; #pragma unroll
;         for (int bj = 0; bj < 2; ++bj)
; #pragma unroll
;           for (int n = 0; n < 2; ++n) {
;             const int col = colb + bj * 128 + n * 16;
;             const f32x4 gg = *(const f32x4*)(g.ln_g + col), bb = *(const f32x4*)(g.ln_b + col);
;             const f32x4 o = (acc[ai][bj][m][n] - mean) * rs * gg + bb;
;             const size_t idx = (size_t)row * 2048 + col;
;             if (g.outf) *(f32x4*)(g.outf + idx) = o;
;             uint2 ob; ob.x = pk2(o[0], o[1]); ob.y = pk2(o[2], o[3]);
;             *(uint2*)(g.outb + idx) = ob;
;           }
;       }
.LBB0_133:
	v_lshl_add_u64 v[28:29], v[160:161], 0, v[122:123]
	s_nop 0
	v_cvt_pk_bf16_f32 v2, v2, v3
	v_cvt_pk_bf16_f32 v3, v4, v5
	v_lshl_add_u64 v[4:5], v[28:29], 1, s[66:67]
	global_store_dwordx2 v[4:5], v[2:3], off
	v_mov_b64_e32 v[2:3], v[232:233]
	v_mov_b64_e32 v[4:5], v[234:235]
	s_nop 0
	v_mov_b64_e32 v[36:37], v[248:249]
	v_mov_b64_e32 v[38:39], v[250:251]
	v_sub_f32_e32 v23, v23, v34
	v_sub_f32_e32 v22, v22, v34
	v_sub_f32_e32 v25, v25, v34
	v_sub_f32_e32 v24, v24, v34
	v_pk_mul_f32 v[24:25], v[26:27], v[24:25]
	v_pk_mul_f32 v[22:23], v[32:33], v[22:23]
	s_and_b64 vcc, exec, s[6:7]
	v_pk_fma_f32 v[2:3], v[22:23], v[2:3], v[36:37]
	v_pk_fma_f32 v[4:5], v[24:25], v[4:5], v[38:39]
	s_cbranch_vccnz .LBB0_135
	global_store_dwordx4 v[30:31], v[2:5], off offset:512
.LBB0_135:
	v_lshl_add_u64 v[22:23], v[160:161], 0, v[118:119]
	s_nop 0
	v_cvt_pk_bf16_f32 v2, v2, v3
	v_cvt_pk_bf16_f32 v3, v4, v5
	v_lshl_add_u64 v[4:5], v[22:23], 1, s[66:67]
	global_store_dwordx2 v[4:5], v[2:3], off
	v_mov_b64_e32 v[2:3], v[236:237]
	v_mov_b64_e32 v[4:5], v[238:239]
	s_nop 0
	v_mov_b64_e32 v[22:23], v[194:195]
	v_mov_b64_e32 v[24:25], v[196:197]
	v_sub_f32_e32 v19, v19, v34
	v_sub_f32_e32 v18, v18, v34
	v_sub_f32_e32 v21, v21, v34
	v_sub_f32_e32 v20, v20, v34
	v_mov_b32_e32 v34, v35
	v_pk_mul_f32 v[20:21], v[34:35], v[20:21]
	v_pk_mul_f32 v[18:19], v[32:33], v[18:19]
	s_and_b64 vcc, exec, s[6:7]
	v_pk_fma_f32 v[2:3], v[18:19], v[2:3], v[22:23]
	v_pk_fma_f32 v[4:5], v[20:21], v[4:5], v[24:25]
	s_cbranch_vccnz .LBB0_137
	global_store_dwordx4 v[30:31], v[2:5], off offset:576
.LBB0_137:
	v_lshl_add_u64 v[18:19], v[160:161], 0, v[114:115]
	s_nop 0
	v_cvt_pk_bf16_f32 v2, v2, v3
	v_cvt_pk_bf16_f32 v3, v4, v5
	v_lshl_add_u64 v[4:5], v[18:19], 1, s[66:67]
	global_store_dwordx2 v[4:5], v[2:3], off
	v_mov_b64_e32 v[2:3], v[224:225]
	v_mov_b64_e32 v[4:5], v[226:227]
	s_nop 0
	v_mov_b64_e32 v[20:21], v[240:241]
	v_mov_b64_e32 v[22:23], v[242:243]
	ds_read_b64 v[18:19], v0 offset:9600
	s_and_b64 vcc, exec, s[6:7]
	s_waitcnt lgkmcnt(0)
	v_sub_f32_e32 v15, v15, v18
	v_sub_f32_e32 v14, v14, v18
	v_sub_f32_e32 v17, v17, v18
	v_sub_f32_e32 v16, v16, v18
	v_pk_mul_f32 v[16:17], v[18:19], v[16:17] op_sel:[1,0]
	v_pk_mul_f32 v[14:15], v[18:19], v[14:15] op_sel:[1,0]
	v_pk_fma_f32 v[4:5], v[4:5], v[16:17], v[22:23]
	v_pk_fma_f32 v[2:3], v[2:3], v[14:15], v[20:21]
	v_lshl_add_u64 v[14:15], v[180:181], 2, s[88:89]
	s_cbranch_vccnz .LBB0_139
	global_store_dwordx4 v[14:15], v[2:5], off
.LBB0_139:
	s_nop 1
	v_cvt_pk_bf16_f32 v2, v2, v3
	v_cvt_pk_bf16_f32 v3, v4, v5
	global_store_dwordx2 v[178:179], v[2:3], off
	v_mov_b64_e32 v[2:3], v[228:229]
	v_mov_b64_e32 v[4:5], v[230:231]
	s_nop 0
	v_mov_b64_e32 v[20:21], v[244:245]
	v_mov_b64_e32 v[22:23], v[246:247]
	v_mov_b32_e32 v16, v19
	v_mov_b32_e32 v17, v19
	v_sub_f32_e32 v25, v11, v18
	v_sub_f32_e32 v24, v10, v18
	v_sub_f32_e32 v13, v13, v18
	v_sub_f32_e32 v12, v12, v18
	v_mov_b32_e32 v10, v19
	v_mov_b32_e32 v11, v19
	v_pk_mul_f32 v[12:13], v[10:11], v[12:13]
	v_pk_mul_f32 v[24:25], v[16:17], v[24:25]
	s_and_b64 vcc, exec, s[6:7]
	v_pk_fma_f32 v[2:3], v[24:25], v[2:3], v[20:21]
	v_pk_fma_f32 v[4:5], v[12:13], v[4:5], v[22:23]
	s_cbranch_vccnz .LBB0_141
	global_store_dwordx4 v[14:15], v[2:5], off offset:64
.LBB0_141:
	v_lshl_add_u64 v[12:13], v[176:177], 0, v[122:123]
	s_nop 0
	v_cvt_pk_bf16_f32 v2, v2, v3
	v_cvt_pk_bf16_f32 v3, v4, v5
	v_lshl_add_u64 v[4:5], v[12:13], 1, s[66:67]
	global_store_dwordx2 v[4:5], v[2:3], off
	v_mov_b64_e32 v[2:3], v[232:233]
	v_mov_b64_e32 v[4:5], v[234:235]
	s_nop 0
	v_mov_b64_e32 v[20:21], v[248:249]
	v_mov_b64_e32 v[22:23], v[250:251]
	v_sub_f32_e32 v7, v7, v18
	v_sub_f32_e32 v6, v6, v18
	v_sub_f32_e32 v9, v9, v18
	v_sub_f32_e32 v8, v8, v18
	v_pk_mul_f32 v[8:9], v[10:11], v[8:9]
	v_pk_mul_f32 v[6:7], v[16:17], v[6:7]
	s_and_b64 vcc, exec, s[6:7]
	v_pk_fma_f32 v[2:3], v[6:7], v[2:3], v[20:21]
	v_pk_fma_f32 v[4:5], v[8:9], v[4:5], v[22:23]
	s_cbranch_vccnz .LBB0_143
	global_store_dwordx4 v[14:15], v[2:5], off offset:512
.LBB0_143:
	v_lshl_add_u64 v[6:7], v[176:177], 0, v[118:119]
	s_nop 0
	v_cvt_pk_bf16_f32 v2, v2, v3
	v_cvt_pk_bf16_f32 v3, v4, v5
	v_lshl_add_u64 v[4:5], v[6:7], 1, s[66:67]
	global_store_dwordx2 v[4:5], v[2:3], off
	v_mov_b64_e32 v[2:3], v[236:237]
	v_mov_b64_e32 v[4:5], v[238:239]
	s_nop 0
	v_mov_b64_e32 v[6:7], v[194:195]
	v_mov_b64_e32 v[8:9], v[196:197]
	v_sub_f32_e32 v11, v185, v18
	v_sub_f32_e32 v10, v184, v18
	v_sub_f32_e32 v13, v183, v18
	v_sub_f32_e32 v12, v182, v18
	v_mov_b32_e32 v18, v19
	v_pk_mul_f32 v[12:13], v[18:19], v[12:13]
	v_pk_mul_f32 v[10:11], v[16:17], v[10:11]
	s_and_b64 vcc, exec, s[6:7]
	v_pk_fma_f32 v[2:3], v[10:11], v[2:3], v[6:7]
	v_pk_fma_f32 v[4:5], v[12:13], v[4:5], v[8:9]
	s_cbranch_vccnz .LBB0_42
	global_store_dwordx4 v[14:15], v[2:5], off offset:576
	s_branch .LBB0_42

; template <int EPI>
; DI void gemm_unit(const GemmP& g, int pm, int pn) {
;     ...
;     __syncthreads();
; #pragma unroll
;     for (int ai = 0; ai < 2; ++ai)
; #pragma unroll
;       for (int m = 0; m < 4; ++m) {
;         const int rl = ai * 128 + wr * 64 + m * 16 + fr;
;         const float mean = mr[rl * 2], rs = mr[rl * 2 + 1];
;         const int row = row0 + ai * 128 + m * 16;
; #pragma unroll
;         for (int bj = 0; bj < 2; ++bj)
; #pragma unroll
;           for (int n = 0; n < 2; ++n) {
;             const int col = colb + bj * 128 + n * 16;
;             const f32x4 gg = *(const f32x4*)(g.ln_g + col), bb = *(const f32x4*)(g.ln_b + col);
;             const f32x4 o = (acc[ai][bj][m][n] - mean) * rs * gg + bb;
;             const size_t idx = (size_t)row * 2048 + col;
;             if (g.outf) *(f32x4*)(g.outf + idx) = o;
;             uint2 ob; ob.x = pk2(o[0], o[1]); ob.y = pk2(o[2], o[3]);
;             *(uint2*)(g.outb + idx) = ob;
;           }
;       }
.LBB0_162:
	s_or_b64 exec, exec, s[6:7]
	v_lshlrev_b64 v[134:135], 2, v[134:135]
	v_lshl_add_u64 v[130:131], s[8:9], 0, v[134:135]
	v_lshl_add_u64 v[134:135], s[10:11], 0, v[134:135]
	global_load_dwordx4 v[224:227], v[130:131], off
	global_load_dwordx4 v[228:231], v[130:131], off offset:64
	global_load_dwordx4 v[232:235], v[130:131], off offset:512
	global_load_dwordx4 v[236:239], v[130:131], off offset:576
	global_load_dwordx4 v[240:243], v[134:135], off
	global_load_dwordx4 v[244:247], v[134:135], off offset:64
	global_load_dwordx4 v[248:251], v[134:135], off offset:512
	global_load_dwordx4 v[194:197], v[134:135], off offset:576
	s_waitcnt lgkmcnt(0)
	s_barrier
	s_waitcnt vmcnt(0)
	v_mov_b64_e32 v[150:151], v[224:225]
	v_mov_b64_e32 v[152:153], v[226:227]
	v_mov_b64_e32 v[154:155], v[240:241]
	v_mov_b64_e32 v[156:157], v[242:243]
	v_lshl_add_u32 v0, v0, 3, 0
	v_add_u32_e32 v162, 0x2000, v0
	ds_read2_b64 v[158:161], v162 offset1:16
	s_mov_b32 s27, 32
	s_mov_b64 s[24:25], 0
	s_and_b64 vcc, exec, s[22:23]
	s_waitcnt lgkmcnt(0)
	v_sub_f32_e32 v129, v129, v158
	v_sub_f32_e32 v128, v128, v158
	v_sub_f32_e32 v127, v127, v158
	v_sub_f32_e32 v126, v126, v158
	v_pk_mul_f32 v[126:127], v[158:159], v[126:127] op_sel:[1,0]
	v_pk_mul_f32 v[128:129], v[158:159], v[128:129] op_sel:[1,0]
	v_sub_f32_e32 v125, v125, v158
	v_sub_f32_e32 v124, v124, v158
	v_sub_f32_e32 v123, v123, v158
	v_sub_f32_e32 v122, v122, v158
	v_pk_mul_f32 v[122:123], v[158:159], v[122:123] op_sel:[1,0]
	v_pk_mul_f32 v[124:125], v[158:159], v[124:125] op_sel:[1,0]
	v_sub_f32_e32 v121, v121, v158
	v_sub_f32_e32 v120, v120, v158
	v_sub_f32_e32 v119, v119, v158
	v_sub_f32_e32 v118, v118, v158
	v_pk_mul_f32 v[118:119], v[158:159], v[118:119] op_sel:[1,0]
	v_pk_mul_f32 v[120:121], v[158:159], v[120:121] op_sel:[1,0]
	v_sub_f32_e32 v117, v117, v158
	v_sub_f32_e32 v116, v116, v158
	v_sub_f32_e32 v115, v115, v158
	v_sub_f32_e32 v114, v114, v158
	v_pk_mul_f32 v[114:115], v[158:159], v[114:115] op_sel:[1,0]
	v_pk_mul_f32 v[116:117], v[158:159], v[116:117] op_sel:[1,0]
	v_sub_f32_e32 v113, v113, v160
	v_sub_f32_e32 v112, v112, v160
	v_sub_f32_e32 v111, v111, v160
	v_sub_f32_e32 v110, v110, v160
	v_pk_mul_f32 v[110:111], v[160:161], v[110:111] op_sel:[1,0]
	v_pk_mul_f32 v[112:113], v[160:161], v[112:113] op_sel:[1,0]
	v_sub_f32_e32 v109, v109, v160
	v_sub_f32_e32 v108, v108, v160
	v_sub_f32_e32 v107, v107, v160
	v_sub_f32_e32 v106, v106, v160
	v_pk_mul_f32 v[106:107], v[160:161], v[106:107] op_sel:[1,0]
	v_pk_mul_f32 v[108:109], v[160:161], v[108:109] op_sel:[1,0]
	v_sub_f32_e32 v105, v105, v160
	v_sub_f32_e32 v104, v104, v160
	v_sub_f32_e32 v103, v103, v160
	v_sub_f32_e32 v102, v102, v160
	v_pk_mul_f32 v[102:103], v[160:161], v[102:103] op_sel:[1,0]
	v_pk_mul_f32 v[104:105], v[160:161], v[104:105] op_sel:[1,0]
	v_sub_f32_e32 v101, v101, v160
	v_sub_f32_e32 v100, v100, v160
	v_sub_f32_e32 v99, v99, v160
	v_sub_f32_e32 v98, v98, v160
	v_pk_mul_f32 v[98:99], v[160:161], v[98:99] op_sel:[1,0]
	v_pk_mul_f32 v[100:101], v[160:161], v[100:101] op_sel:[1,0]
	v_pk_fma_f32 v[128:129], v[152:153], v[128:129], v[156:157]
	v_pk_fma_f32 v[126:127], v[150:151], v[126:127], v[154:155]
	s_nop 0
	v_cvt_pk_bf16_f32 v126, v126, v127
	v_cvt_pk_bf16_f32 v127, v128, v129
	global_store_dwordx2 v[132:133], v[126:127], off
	v_mov_b64_e32 v[126:127], v[228:229]
	v_mov_b64_e32 v[128:129], v[230:231]
	s_nop 0
	v_mov_b64_e32 v[150:151], v[244:245]
	v_mov_b64_e32 v[152:153], v[246:247]
	v_pk_fma_f32 v[124:125], v[124:125], v[128:129], v[152:153]
	v_pk_fma_f32 v[122:123], v[122:123], v[126:127], v[150:151]
	s_nop 0
	v_cvt_pk_bf16_f32 v122, v122, v123
	v_cvt_pk_bf16_f32 v123, v124, v125
	global_store_dwordx2 v[132:133], v[122:123], off offset:32
	v_mov_b64_e32 v[122:123], v[232:233]
	v_mov_b64_e32 v[124:125], v[234:235]
	s_nop 0
	v_mov_b64_e32 v[126:127], v[248:249]
	v_mov_b64_e32 v[128:129], v[250:251]
	v_pk_fma_f32 v[120:121], v[120:121], v[124:125], v[128:129]
	v_pk_fma_f32 v[118:119], v[118:119], v[122:123], v[126:127]
	s_nop 0
	v_cvt_pk_bf16_f32 v118, v118, v119
	v_cvt_pk_bf16_f32 v119, v120, v121
	global_store_dwordx2 v[132:133], v[118:119], off offset:256
	v_mov_b64_e32 v[118:119], v[236:237]
	v_mov_b64_e32 v[120:121], v[238:239]
	s_nop 0
	v_mov_b64_e32 v[122:123], v[194:195]
	v_mov_b64_e32 v[124:125], v[196:197]
	v_pk_fma_f32 v[116:117], v[116:117], v[120:121], v[124:125]
	v_pk_fma_f32 v[114:115], v[114:115], v[118:119], v[122:123]
	s_nop 0
	v_cvt_pk_bf16_f32 v114, v114, v115
	v_cvt_pk_bf16_f32 v115, v116, v117
	global_store_dwordx2 v[132:133], v[114:115], off offset:288
	v_mov_b64_e32 v[114:115], v[224:225]
	v_mov_b64_e32 v[116:117], v[226:227]
	s_nop 0
	v_mov_b64_e32 v[118:119], v[240:241]
	v_mov_b64_e32 v[120:121], v[242:243]
	v_pk_fma_f32 v[112:113], v[116:117], v[112:113], v[120:121]
	v_pk_fma_f32 v[110:111], v[114:115], v[110:111], v[118:119]
	s_nop 0
	v_cvt_pk_bf16_f32 v110, v110, v111
	v_cvt_pk_bf16_f32 v111, v112, v113
	global_store_dwordx2 v[136:137], v[110:111], off
	v_mov_b64_e32 v[110:111], v[228:229]
	v_mov_b64_e32 v[112:113], v[230:231]
	s_nop 0
	v_mov_b64_e32 v[114:115], v[244:245]
	v_mov_b64_e32 v[116:117], v[246:247]
	v_pk_fma_f32 v[108:109], v[108:109], v[112:113], v[116:117]
	v_pk_fma_f32 v[106:107], v[106:107], v[110:111], v[114:115]
	s_nop 0
	v_cvt_pk_bf16_f32 v106, v106, v107
	v_cvt_pk_bf16_f32 v107, v108, v109
	global_store_dwordx2 v[136:137], v[106:107], off offset:32
	v_mov_b64_e32 v[106:107], v[232:233]
	v_mov_b64_e32 v[108:109], v[234:235]
	s_nop 0
	v_mov_b64_e32 v[110:111], v[248:249]
	v_mov_b64_e32 v[112:113], v[250:251]
	v_pk_fma_f32 v[104:105], v[104:105], v[108:109], v[112:113]
	v_pk_fma_f32 v[102:103], v[102:103], v[106:107], v[110:111]
	s_nop 0
	v_cvt_pk_bf16_f32 v102, v102, v103
	v_cvt_pk_bf16_f32 v103, v104, v105
	global_store_dwordx2 v[136:137], v[102:103], off offset:256
	v_mov_b64_e32 v[102:103], v[236:237]
	v_mov_b64_e32 v[104:105], v[238:239]
	s_nop 0
	v_mov_b64_e32 v[106:107], v[194:195]
	v_mov_b64_e32 v[108:109], v[196:197]
	v_pk_fma_f32 v[100:101], v[100:101], v[104:105], v[108:109]
	v_pk_fma_f32 v[98:99], v[98:99], v[102:103], v[106:107]
	s_nop 0
	v_cvt_pk_bf16_f32 v98, v98, v99
	v_cvt_pk_bf16_f32 v99, v100, v101
	global_store_dwordx2 v[136:137], v[98:99], off offset:288
	v_mov_b64_e32 v[98:99], v[224:225]
	v_mov_b64_e32 v[100:101], v[226:227]
	s_nop 0
	v_mov_b64_e32 v[102:103], v[240:241]
	v_mov_b64_e32 v[104:105], v[242:243]
	ds_read2_b64 v[106:109], v162 offset0:32 offset1:48
	s_waitcnt lgkmcnt(0)
; template <int EPI>
; DI void gemm_unit(const GemmP& g, int pm, int pn) {
;     ...
; #pragma unroll
;     for (int ai = 0; ai < 2; ++ai)
; #pragma unroll
;       for (int m = 0; m < 4; ++m) {
;         const int rl = ai * 128 + wr * 64 + m * 16 + fr;
;         const float mean = mr[rl * 2], rs = mr[rl * 2 + 1];
;         const int row = row0 + ai * 128 + m * 16;
; #pragma unroll
;         for (int bj = 0; bj < 2; ++bj)
; #pragma unroll
;           for (int n = 0; n < 2; ++n) {
;             const int col = colb + bj * 128 + n * 16;
;             const f32x4 gg = *(const f32x4*)(g.ln_g + col), bb = *(const f32x4*)(g.ln_b + col);
;             const f32x4 o = (acc[ai][bj][m][n] - mean) * rs * gg + bb;
;             const size_t idx = (size_t)row * 2048 + col;
;             if (g.outf) *(f32x4*)(g.outf + idx) = o;
;             uint2 ob; ob.x = pk2(o[0], o[1]); ob.y = pk2(o[2], o[3]);
;             *(uint2*)(g.outb + idx) = ob;
;           }
;       }
	v_sub_f32_e32 v97, v97, v106
	v_sub_f32_e32 v96, v96, v106
	v_sub_f32_e32 v95, v95, v106
	v_sub_f32_e32 v94, v94, v106
	v_pk_mul_f32 v[94:95], v[106:107], v[94:95] op_sel:[1,0]
	v_pk_mul_f32 v[96:97], v[106:107], v[96:97] op_sel:[1,0]
	v_sub_f32_e32 v93, v93, v106
	v_sub_f32_e32 v92, v92, v106
	v_sub_f32_e32 v91, v91, v106
	v_sub_f32_e32 v90, v90, v106
	v_pk_mul_f32 v[90:91], v[106:107], v[90:91] op_sel:[1,0]
	v_pk_mul_f32 v[92:93], v[106:107], v[92:93] op_sel:[1,0]
	v_sub_f32_e32 v89, v89, v106
	v_sub_f32_e32 v88, v88, v106
	v_sub_f32_e32 v87, v87, v106
	v_sub_f32_e32 v86, v86, v106
	v_pk_mul_f32 v[86:87], v[106:107], v[86:87] op_sel:[1,0]
	v_pk_mul_f32 v[88:89], v[106:107], v[88:89] op_sel:[1,0]
	v_sub_f32_e32 v85, v85, v106
	v_sub_f32_e32 v84, v84, v106
	v_sub_f32_e32 v83, v83, v106
	v_sub_f32_e32 v82, v82, v106
	v_pk_mul_f32 v[82:83], v[106:107], v[82:83] op_sel:[1,0]
	v_pk_mul_f32 v[84:85], v[106:107], v[84:85] op_sel:[1,0]
	v_sub_f32_e32 v81, v81, v108
	v_sub_f32_e32 v80, v80, v108
	v_sub_f32_e32 v79, v79, v108
	v_sub_f32_e32 v78, v78, v108
	v_pk_mul_f32 v[78:79], v[108:109], v[78:79] op_sel:[1,0]
	v_pk_mul_f32 v[80:81], v[108:109], v[80:81] op_sel:[1,0]
	v_sub_f32_e32 v77, v77, v108
	v_sub_f32_e32 v76, v76, v108
	v_sub_f32_e32 v75, v75, v108
	v_sub_f32_e32 v74, v74, v108
	v_pk_mul_f32 v[74:75], v[108:109], v[74:75] op_sel:[1,0]
	v_pk_mul_f32 v[76:77], v[108:109], v[76:77] op_sel:[1,0]
	v_sub_f32_e32 v73, v73, v108
	v_sub_f32_e32 v72, v72, v108
	v_sub_f32_e32 v71, v71, v108
	v_sub_f32_e32 v70, v70, v108
	v_pk_mul_f32 v[70:71], v[108:109], v[70:71] op_sel:[1,0]
	v_pk_mul_f32 v[72:73], v[108:109], v[72:73] op_sel:[1,0]
	v_sub_f32_e32 v69, v69, v108
	v_sub_f32_e32 v68, v68, v108
	v_sub_f32_e32 v67, v67, v108
	v_sub_f32_e32 v66, v66, v108
	v_pk_mul_f32 v[66:67], v[108:109], v[66:67] op_sel:[1,0]
	v_pk_mul_f32 v[68:69], v[108:109], v[68:69] op_sel:[1,0]
	v_pk_fma_f32 v[96:97], v[100:101], v[96:97], v[104:105]
	v_pk_fma_f32 v[94:95], v[98:99], v[94:95], v[102:103]
	s_nop 0
	v_cvt_pk_bf16_f32 v94, v94, v95
	v_cvt_pk_bf16_f32 v95, v96, v97
	global_store_dwordx2 v[138:139], v[94:95], off
	v_mov_b64_e32 v[94:95], v[228:229]
	v_mov_b64_e32 v[96:97], v[230:231]
	s_nop 0
	v_mov_b64_e32 v[98:99], v[244:245]
	v_mov_b64_e32 v[100:101], v[246:247]
	v_pk_fma_f32 v[92:93], v[92:93], v[96:97], v[100:101]
	v_pk_fma_f32 v[90:91], v[90:91], v[94:95], v[98:99]
	s_nop 0
	v_cvt_pk_bf16_f32 v90, v90, v91
	v_cvt_pk_bf16_f32 v91, v92, v93
	global_store_dwordx2 v[138:139], v[90:91], off offset:32
	v_mov_b64_e32 v[90:91], v[232:233]
	v_mov_b64_e32 v[92:93], v[234:235]
	s_nop 0
	v_mov_b64_e32 v[94:95], v[248:249]
	v_mov_b64_e32 v[96:97], v[250:251]
	v_pk_fma_f32 v[88:89], v[88:89], v[92:93], v[96:97]
	v_pk_fma_f32 v[86:87], v[86:87], v[90:91], v[94:95]
	s_nop 0
	v_cvt_pk_bf16_f32 v86, v86, v87
	v_cvt_pk_bf16_f32 v87, v88, v89
	global_store_dwordx2 v[138:139], v[86:87], off offset:256
	v_mov_b64_e32 v[86:87], v[236:237]
	v_mov_b64_e32 v[88:89], v[238:239]
	s_nop 0
	v_mov_b64_e32 v[90:91], v[194:195]
	v_mov_b64_e32 v[92:93], v[196:197]
	v_pk_fma_f32 v[84:85], v[84:85], v[88:89], v[92:93]
	v_pk_fma_f32 v[82:83], v[82:83], v[86:87], v[90:91]
	s_nop 0
	v_cvt_pk_bf16_f32 v82, v82, v83
	v_cvt_pk_bf16_f32 v83, v84, v85
	global_store_dwordx2 v[138:139], v[82:83], off offset:288
	v_mov_b64_e32 v[82:83], v[224:225]
	v_mov_b64_e32 v[84:85], v[226:227]
	s_nop 0
	v_mov_b64_e32 v[86:87], v[240:241]
	v_mov_b64_e32 v[88:89], v[242:243]
	v_pk_fma_f32 v[80:81], v[84:85], v[80:81], v[88:89]
	v_pk_fma_f32 v[78:79], v[82:83], v[78:79], v[86:87]
	s_nop 0
	v_cvt_pk_bf16_f32 v78, v78, v79
	v_cvt_pk_bf16_f32 v79, v80, v81
	global_store_dwordx2 v[140:141], v[78:79], off
	v_mov_b64_e32 v[78:79], v[228:229]
	v_mov_b64_e32 v[80:81], v[230:231]
	s_nop 0
	v_mov_b64_e32 v[82:83], v[244:245]
	v_mov_b64_e32 v[84:85], v[246:247]
	v_pk_fma_f32 v[76:77], v[76:77], v[80:81], v[84:85]
	v_pk_fma_f32 v[74:75], v[74:75], v[78:79], v[82:83]
	s_nop 0
	v_cvt_pk_bf16_f32 v74, v74, v75
	v_cvt_pk_bf16_f32 v75, v76, v77
	global_store_dwordx2 v[140:141], v[74:75], off offset:32
	v_mov_b64_e32 v[74:75], v[232:233]
	v_mov_b64_e32 v[76:77], v[234:235]
	s_nop 0
	v_mov_b64_e32 v[78:79], v[248:249]
	v_mov_b64_e32 v[80:81], v[250:251]
	v_pk_fma_f32 v[72:73], v[72:73], v[76:77], v[80:81]
	v_pk_fma_f32 v[70:71], v[70:71], v[74:75], v[78:79]
	s_nop 0
	v_cvt_pk_bf16_f32 v70, v70, v71
	v_cvt_pk_bf16_f32 v71, v72, v73
	global_store_dwordx2 v[140:141], v[70:71], off offset:256
	v_mov_b64_e32 v[70:71], v[236:237]
	v_mov_b64_e32 v[72:73], v[238:239]
	s_nop 0
	v_mov_b64_e32 v[74:75], v[194:195]
	v_mov_b64_e32 v[76:77], v[196:197]
	v_pk_fma_f32 v[68:69], v[68:69], v[72:73], v[76:77]
	v_pk_fma_f32 v[66:67], v[66:67], v[70:71], v[74:75]
	v_lshl_add_u32 v74, v171, 3, 0
	v_cvt_pk_bf16_f32 v66, v66, v67
	v_cvt_pk_bf16_f32 v67, v68, v69
	global_store_dwordx2 v[140:141], v[66:67], off offset:288
	v_mov_b64_e32 v[66:67], v[224:225]
	v_mov_b64_e32 v[68:69], v[226:227]
	s_nop 0
	v_mov_b64_e32 v[70:71], v[240:241]
	v_mov_b64_e32 v[72:73], v[242:243]
	ds_read_b64 v[74:75], v74 offset:8192
	s_waitcnt lgkmcnt(0)
; template <int EPI>
; DI void gemm_unit(const GemmP& g, int pm, int pn) {
;     ...
; #pragma unroll
;     for (int ai = 0; ai < 2; ++ai)
; #pragma unroll
;       for (int m = 0; m < 4; ++m) {
;         const int rl = ai * 128 + wr * 64 + m * 16 + fr;
;         const float mean = mr[rl * 2], rs = mr[rl * 2 + 1];
;         const int row = row0 + ai * 128 + m * 16;
; #pragma unroll
;         for (int bj = 0; bj < 2; ++bj)
; #pragma unroll
;           for (int n = 0; n < 2; ++n) {
;             const int col = colb + bj * 128 + n * 16;
;             const f32x4 gg = *(const f32x4*)(g.ln_g + col), bb = *(const f32x4*)(g.ln_b + col);
;             const f32x4 o = (acc[ai][bj][m][n] - mean) * rs * gg + bb;
;             const size_t idx = (size_t)row * 2048 + col;
;             if (g.outf) *(f32x4*)(g.outf + idx) = o;
;             uint2 ob; ob.x = pk2(o[0], o[1]); ob.y = pk2(o[2], o[3]);
;             *(uint2*)(g.outb + idx) = ob;
;           }
;       }
	v_sub_f32_e32 v65, v65, v74
	v_sub_f32_e32 v64, v64, v74
	v_sub_f32_e32 v63, v63, v74
	v_sub_f32_e32 v62, v62, v74
	v_pk_mul_f32 v[62:63], v[74:75], v[62:63] op_sel:[1,0]
	v_pk_mul_f32 v[64:65], v[74:75], v[64:65] op_sel:[1,0]
	v_sub_f32_e32 v61, v61, v74
	v_sub_f32_e32 v60, v60, v74
	v_sub_f32_e32 v59, v59, v74
	v_sub_f32_e32 v58, v58, v74
	v_pk_mul_f32 v[58:59], v[74:75], v[58:59] op_sel:[1,0]
	v_pk_mul_f32 v[60:61], v[74:75], v[60:61] op_sel:[1,0]
	v_sub_f32_e32 v57, v57, v74
	v_sub_f32_e32 v56, v56, v74
	v_sub_f32_e32 v55, v55, v74
	v_sub_f32_e32 v54, v54, v74
	v_pk_mul_f32 v[54:55], v[74:75], v[54:55] op_sel:[1,0]
	v_pk_mul_f32 v[56:57], v[74:75], v[56:57] op_sel:[1,0]
	v_sub_f32_e32 v53, v53, v74
	v_sub_f32_e32 v52, v52, v74
	v_sub_f32_e32 v51, v51, v74
	v_sub_f32_e32 v50, v50, v74
	v_pk_mul_f32 v[50:51], v[74:75], v[50:51] op_sel:[1,0]
	v_pk_mul_f32 v[52:53], v[74:75], v[52:53] op_sel:[1,0]
	v_pk_fma_f32 v[64:65], v[68:69], v[64:65], v[72:73]
	v_pk_fma_f32 v[62:63], v[66:67], v[62:63], v[70:71]
	s_nop 0
	v_cvt_pk_bf16_f32 v62, v62, v63
	v_cvt_pk_bf16_f32 v63, v64, v65
	global_store_dwordx2 v[144:145], v[62:63], off
	v_mov_b64_e32 v[62:63], v[228:229]
	v_mov_b64_e32 v[64:65], v[230:231]
	s_nop 0
	v_mov_b64_e32 v[66:67], v[244:245]
	v_mov_b64_e32 v[68:69], v[246:247]
	v_pk_fma_f32 v[60:61], v[60:61], v[64:65], v[68:69]
	v_pk_fma_f32 v[58:59], v[58:59], v[62:63], v[66:67]
	s_nop 0
	v_cvt_pk_bf16_f32 v58, v58, v59
	v_cvt_pk_bf16_f32 v59, v60, v61
	global_store_dwordx2 v[144:145], v[58:59], off offset:32
	v_mov_b64_e32 v[58:59], v[232:233]
	v_mov_b64_e32 v[60:61], v[234:235]
	s_nop 0
	v_mov_b64_e32 v[62:63], v[248:249]
	v_mov_b64_e32 v[64:65], v[250:251]
	v_pk_fma_f32 v[56:57], v[56:57], v[60:61], v[64:65]
	v_pk_fma_f32 v[54:55], v[54:55], v[58:59], v[62:63]
	s_nop 0
	v_cvt_pk_bf16_f32 v54, v54, v55
	v_cvt_pk_bf16_f32 v55, v56, v57
	global_store_dwordx2 v[144:145], v[54:55], off offset:256
	v_mov_b64_e32 v[54:55], v[236:237]
	v_mov_b64_e32 v[56:57], v[238:239]
	s_nop 0
	v_mov_b64_e32 v[58:59], v[194:195]
	v_mov_b64_e32 v[60:61], v[196:197]
	v_pk_fma_f32 v[52:53], v[52:53], v[56:57], v[60:61]
	v_pk_fma_f32 v[50:51], v[50:51], v[54:55], v[58:59]
	s_nop 0
	v_cvt_pk_bf16_f32 v50, v50, v51
	v_cvt_pk_bf16_f32 v51, v52, v53
	global_store_dwordx2 v[144:145], v[50:51], off offset:288
	v_mov_b64_e32 v[50:51], v[224:225]
	v_mov_b64_e32 v[52:53], v[226:227]
	s_nop 0
	v_mov_b64_e32 v[54:55], v[240:241]
	v_mov_b64_e32 v[56:57], v[242:243]
	ds_read2_b64 v[58:61], v162 offset0:144 offset1:160
	s_waitcnt lgkmcnt(0)
	v_sub_f32_e32 v49, v49, v58
	v_sub_f32_e32 v48, v48, v58
	v_sub_f32_e32 v47, v47, v58
	v_sub_f32_e32 v46, v46, v58
	v_pk_mul_f32 v[46:47], v[58:59], v[46:47] op_sel:[1,0]
	v_pk_mul_f32 v[48:49], v[58:59], v[48:49] op_sel:[1,0]
	v_sub_f32_e32 v45, v45, v58
	v_sub_f32_e32 v44, v44, v58
	v_sub_f32_e32 v43, v43, v58
	v_sub_f32_e32 v42, v42, v58
	v_pk_mul_f32 v[42:43], v[58:59], v[42:43] op_sel:[1,0]
	v_pk_mul_f32 v[44:45], v[58:59], v[44:45] op_sel:[1,0]
	v_sub_f32_e32 v41, v41, v58
	v_sub_f32_e32 v40, v40, v58
	v_sub_f32_e32 v39, v39, v58
	v_sub_f32_e32 v38, v38, v58
	v_pk_mul_f32 v[38:39], v[58:59], v[38:39] op_sel:[1,0]
	v_pk_mul_f32 v[40:41], v[58:59], v[40:41] op_sel:[1,0]
	v_sub_f32_e32 v37, v37, v58
	v_sub_f32_e32 v36, v36, v58
	v_sub_f32_e32 v35, v35, v58
	v_sub_f32_e32 v34, v34, v58
	v_pk_mul_f32 v[34:35], v[58:59], v[34:35] op_sel:[1,0]
	v_pk_mul_f32 v[36:37], v[58:59], v[36:37] op_sel:[1,0]
	v_sub_f32_e32 v33, v33, v60
	v_sub_f32_e32 v32, v32, v60
	v_sub_f32_e32 v31, v31, v60
	v_sub_f32_e32 v30, v30, v60
	v_pk_mul_f32 v[30:31], v[60:61], v[30:31] op_sel:[1,0]
	v_pk_mul_f32 v[32:33], v[60:61], v[32:33] op_sel:[1,0]
	v_sub_f32_e32 v29, v29, v60
	v_sub_f32_e32 v28, v28, v60
	v_sub_f32_e32 v27, v27, v60
	v_sub_f32_e32 v26, v26, v60
	v_pk_mul_f32 v[26:27], v[60:61], v[26:27] op_sel:[1,0]
	v_pk_mul_f32 v[28:29], v[60:61], v[28:29] op_sel:[1,0]
	v_sub_f32_e32 v25, v25, v60
	v_sub_f32_e32 v24, v24, v60
	v_sub_f32_e32 v23, v23, v60
	v_sub_f32_e32 v22, v22, v60
	v_pk_mul_f32 v[22:23], v[60:61], v[22:23] op_sel:[1,0]
	v_pk_mul_f32 v[24:25], v[60:61], v[24:25] op_sel:[1,0]
	v_sub_f32_e32 v21, v21, v60
	v_sub_f32_e32 v20, v20, v60
	v_sub_f32_e32 v19, v19, v60
	v_sub_f32_e32 v18, v18, v60
	v_pk_mul_f32 v[18:19], v[60:61], v[18:19] op_sel:[1,0]
	v_pk_mul_f32 v[20:21], v[60:61], v[20:21] op_sel:[1,0]
	v_pk_fma_f32 v[48:49], v[52:53], v[48:49], v[56:57]
	v_pk_fma_f32 v[46:47], v[50:51], v[46:47], v[54:55]
	s_nop 0
	v_cvt_pk_bf16_f32 v46, v46, v47
	v_cvt_pk_bf16_f32 v47, v48, v49
	global_store_dwordx2 v[146:147], v[46:47], off
	v_mov_b64_e32 v[46:47], v[228:229]
	v_mov_b64_e32 v[48:49], v[230:231]
	s_nop 0
	v_mov_b64_e32 v[50:51], v[244:245]
	v_mov_b64_e32 v[52:53], v[246:247]
	v_pk_fma_f32 v[44:45], v[44:45], v[48:49], v[52:53]
	v_pk_fma_f32 v[42:43], v[42:43], v[46:47], v[50:51]
	s_nop 0
	v_cvt_pk_bf16_f32 v42, v42, v43
	v_cvt_pk_bf16_f32 v43, v44, v45
; template <int EPI>
; DI void gemm_unit(const GemmP& g, int pm, int pn) {
;     ...
; #pragma unroll
;     for (int ai = 0; ai < 2; ++ai)
; #pragma unroll
;       for (int m = 0; m < 4; ++m) {
;         const int rl = ai * 128 + wr * 64 + m * 16 + fr;
;         const float mean = mr[rl * 2], rs = mr[rl * 2 + 1];
;         const int row = row0 + ai * 128 + m * 16;
; #pragma unroll
;         for (int bj = 0; bj < 2; ++bj)
; #pragma unroll
;           for (int n = 0; n < 2; ++n) {
;             const int col = colb + bj * 128 + n * 16;
;             const f32x4 gg = *(const f32x4*)(g.ln_g + col), bb = *(const f32x4*)(g.ln_b + col);
;             const f32x4 o = (acc[ai][bj][m][n] - mean) * rs * gg + bb;
;             const size_t idx = (size_t)row * 2048 + col;
;             if (g.outf) *(f32x4*)(g.outf + idx) = o;
;             uint2 ob; ob.x = pk2(o[0], o[1]); ob.y = pk2(o[2], o[3]);
;             *(uint2*)(g.outb + idx) = ob;
;           }
;       }
;     __syncthreads();
	global_store_dwordx2 v[146:147], v[42:43], off offset:32
	v_mov_b64_e32 v[42:43], v[232:233]
	v_mov_b64_e32 v[44:45], v[234:235]
	s_nop 0
	v_mov_b64_e32 v[46:47], v[248:249]
	v_mov_b64_e32 v[48:49], v[250:251]
	v_pk_fma_f32 v[40:41], v[40:41], v[44:45], v[48:49]
	v_pk_fma_f32 v[38:39], v[38:39], v[42:43], v[46:47]
	s_nop 0
	v_cvt_pk_bf16_f32 v38, v38, v39
	v_cvt_pk_bf16_f32 v39, v40, v41
	global_store_dwordx2 v[146:147], v[38:39], off offset:256
	v_mov_b64_e32 v[38:39], v[236:237]
	v_mov_b64_e32 v[40:41], v[238:239]
	s_nop 0
	v_mov_b64_e32 v[42:43], v[194:195]
	v_mov_b64_e32 v[44:45], v[196:197]
	v_pk_fma_f32 v[36:37], v[36:37], v[40:41], v[44:45]
	v_pk_fma_f32 v[34:35], v[34:35], v[38:39], v[42:43]
	s_nop 0
	v_cvt_pk_bf16_f32 v34, v34, v35
	v_cvt_pk_bf16_f32 v35, v36, v37
	global_store_dwordx2 v[146:147], v[34:35], off offset:288
	v_mov_b64_e32 v[34:35], v[224:225]
	v_mov_b64_e32 v[36:37], v[226:227]
	s_nop 0
	v_mov_b64_e32 v[38:39], v[240:241]
	v_mov_b64_e32 v[40:41], v[242:243]
	v_pk_fma_f32 v[32:33], v[36:37], v[32:33], v[40:41]
	v_pk_fma_f32 v[30:31], v[34:35], v[30:31], v[38:39]
	s_nop 0
	v_cvt_pk_bf16_f32 v30, v30, v31
	v_cvt_pk_bf16_f32 v31, v32, v33
	global_store_dwordx2 v[142:143], v[30:31], off
	v_mov_b64_e32 v[30:31], v[228:229]
	v_mov_b64_e32 v[32:33], v[230:231]
	s_nop 0
	v_mov_b64_e32 v[34:35], v[244:245]
	v_mov_b64_e32 v[36:37], v[246:247]
	v_pk_fma_f32 v[28:29], v[28:29], v[32:33], v[36:37]
	v_pk_fma_f32 v[26:27], v[26:27], v[30:31], v[34:35]
	s_nop 0
	v_cvt_pk_bf16_f32 v26, v26, v27
	v_cvt_pk_bf16_f32 v27, v28, v29
	global_store_dwordx2 v[142:143], v[26:27], off offset:32
	v_mov_b64_e32 v[26:27], v[232:233]
	v_mov_b64_e32 v[28:29], v[234:235]
	s_nop 0
	v_mov_b64_e32 v[30:31], v[248:249]
	v_mov_b64_e32 v[32:33], v[250:251]
	v_pk_fma_f32 v[24:25], v[24:25], v[28:29], v[32:33]
	v_pk_fma_f32 v[22:23], v[22:23], v[26:27], v[30:31]
	s_nop 0
	v_cvt_pk_bf16_f32 v22, v22, v23
	v_cvt_pk_bf16_f32 v23, v24, v25
	global_store_dwordx2 v[142:143], v[22:23], off offset:256
	v_mov_b64_e32 v[22:23], v[236:237]
	v_mov_b64_e32 v[24:25], v[238:239]
	s_nop 0
	v_mov_b64_e32 v[26:27], v[194:195]
	v_mov_b64_e32 v[28:29], v[196:197]
	v_pk_fma_f32 v[20:21], v[20:21], v[24:25], v[28:29]
	v_pk_fma_f32 v[18:19], v[18:19], v[22:23], v[26:27]
	s_nop 0
	v_cvt_pk_bf16_f32 v18, v18, v19
	v_cvt_pk_bf16_f32 v19, v20, v21
	global_store_dwordx2 v[142:143], v[18:19], off offset:288
	v_mov_b64_e32 v[18:19], v[224:225]
	v_mov_b64_e32 v[20:21], v[226:227]
	s_nop 0
	v_mov_b64_e32 v[22:23], v[240:241]
	v_mov_b64_e32 v[24:25], v[242:243]
	ds_read_b64 v[26:27], v0 offset:9600
	s_waitcnt lgkmcnt(0)
	v_sub_f32_e32 v17, v17, v26
	v_sub_f32_e32 v16, v16, v26
	v_sub_f32_e32 v15, v15, v26
	v_sub_f32_e32 v14, v14, v26
	v_pk_mul_f32 v[14:15], v[26:27], v[14:15] op_sel:[1,0]
	v_pk_mul_f32 v[16:17], v[26:27], v[16:17] op_sel:[1,0]
	v_sub_f32_e32 v13, v13, v26
	v_sub_f32_e32 v12, v12, v26
	v_sub_f32_e32 v11, v11, v26
	v_sub_f32_e32 v10, v10, v26
	v_pk_mul_f32 v[10:11], v[26:27], v[10:11] op_sel:[1,0]
	v_pk_mul_f32 v[12:13], v[26:27], v[12:13] op_sel:[1,0]
	v_sub_f32_e32 v9, v9, v26
	v_sub_f32_e32 v8, v8, v26
	v_sub_f32_e32 v7, v7, v26
	v_sub_f32_e32 v6, v6, v26
	v_pk_mul_f32 v[6:7], v[26:27], v[6:7] op_sel:[1,0]
	v_pk_mul_f32 v[8:9], v[26:27], v[8:9] op_sel:[1,0]
	v_sub_f32_e32 v5, v5, v26
	v_sub_f32_e32 v4, v4, v26
	v_sub_f32_e32 v3, v3, v26
	v_sub_f32_e32 v2, v2, v26
	v_pk_mul_f32 v[2:3], v[26:27], v[2:3] op_sel:[1,0]
	v_pk_mul_f32 v[4:5], v[26:27], v[4:5] op_sel:[1,0]
	v_pk_fma_f32 v[16:17], v[20:21], v[16:17], v[24:25]
	v_pk_fma_f32 v[14:15], v[18:19], v[14:15], v[22:23]
	s_nop 0
	v_cvt_pk_bf16_f32 v14, v14, v15
	v_cvt_pk_bf16_f32 v15, v16, v17
	global_store_dwordx2 v[148:149], v[14:15], off
	v_mov_b64_e32 v[14:15], v[228:229]
	v_mov_b64_e32 v[16:17], v[230:231]
	s_nop 0
	v_mov_b64_e32 v[18:19], v[244:245]
	v_mov_b64_e32 v[20:21], v[246:247]
	v_pk_fma_f32 v[12:13], v[12:13], v[16:17], v[20:21]
	v_pk_fma_f32 v[10:11], v[10:11], v[14:15], v[18:19]
	s_nop 0
	v_cvt_pk_bf16_f32 v10, v10, v11
	v_cvt_pk_bf16_f32 v11, v12, v13
	global_store_dwordx2 v[148:149], v[10:11], off offset:32
	v_mov_b64_e32 v[10:11], v[232:233]
	v_mov_b64_e32 v[12:13], v[234:235]
	s_nop 0
	v_mov_b64_e32 v[14:15], v[248:249]
	v_mov_b64_e32 v[16:17], v[250:251]
	v_pk_fma_f32 v[8:9], v[8:9], v[12:13], v[16:17]
	v_pk_fma_f32 v[6:7], v[6:7], v[10:11], v[14:15]
	s_nop 0
	v_cvt_pk_bf16_f32 v6, v6, v7
	v_cvt_pk_bf16_f32 v7, v8, v9
	global_store_dwordx2 v[148:149], v[6:7], off offset:256
	v_mov_b64_e32 v[6:7], v[236:237]
	v_mov_b64_e32 v[8:9], v[238:239]
	s_nop 0
	v_mov_b64_e32 v[10:11], v[194:195]
	v_mov_b64_e32 v[12:13], v[196:197]
	v_pk_fma_f32 v[4:5], v[4:5], v[8:9], v[12:13]
	v_pk_fma_f32 v[2:3], v[2:3], v[6:7], v[10:11]
	s_nop 0
	v_cvt_pk_bf16_f32 v2, v2, v3
	v_cvt_pk_bf16_f32 v3, v4, v5
	global_store_dwordx2 v[148:149], v[2:3], off offset:288
	s_barrier
	s_cbranch_vccnz .LBB0_200

; template <int EPI>
; DI void gemm_unit(const GemmP& g, int pm, int pn) {
;     ...
;     __syncthreads();
; #pragma unroll
;     for (int ai = 0; ai < 2; ++ai)
; #pragma unroll
;       for (int m = 0; m < 4; ++m) {
;         const int rl = ai * 128 + wr * 64 + m * 16 + fr;
;         const float mean = mr[rl * 2], rs = mr[rl * 2 + 1];
;         const int row = row0 + ai * 128 + m * 16;
; #pragma unroll
;         for (int bj = 0; bj < 2; ++bj)
; #pragma unroll
;           for (int n = 0; n < 2; ++n) {
;             const int col = colb + bj * 128 + n * 16;
;             const f32x4 gg = *(const f32x4*)(g.ln_g + col), bb = *(const f32x4*)(g.ln_b + col);
;             const f32x4 o = (acc[ai][bj][m][n] - mean) * rs * gg + bb;
;             const size_t idx = (size_t)row * 2048 + col;
;             if (g.outf) *(f32x4*)(g.outf + idx) = o;
;             uint2 ob; ob.x = pk2(o[0], o[1]); ob.y = pk2(o[2], o[3]);
;             *(uint2*)(g.outb + idx) = ob;
;           }
;       }
.LBB0_296:
	s_or_b64 exec, exec, s[6:7]
	v_lshlrev_b64 v[20:21], 2, v[148:149]
	v_lshl_add_u64 v[18:19], s[10:11], 0, v[20:21]
	v_lshl_add_u64 v[20:21], s[12:13], 0, v[20:21]
	global_load_dwordx4 v[224:227], v[18:19], off
	global_load_dwordx4 v[228:231], v[18:19], off offset:64
	global_load_dwordx4 v[232:235], v[18:19], off offset:512
	global_load_dwordx4 v[236:239], v[18:19], off offset:576
	global_load_dwordx4 v[240:243], v[20:21], off
	global_load_dwordx4 v[244:247], v[20:21], off offset:64
	global_load_dwordx4 v[248:251], v[20:21], off offset:512
	global_load_dwordx4 v[194:197], v[20:21], off offset:576
	s_waitcnt lgkmcnt(0)
	s_barrier
	s_waitcnt vmcnt(0)
	v_mov_b64_e32 v[26:27], v[224:225]
	v_mov_b64_e32 v[28:29], v[226:227]
	v_mov_b64_e32 v[30:31], v[240:241]
	v_mov_b64_e32 v[32:33], v[242:243]
	v_lshl_add_u32 v0, v0, 3, 0
	v_add_u32_e32 v24, 0x2000, v0
	ds_read2_b64 v[184:187], v24 offset1:16
	v_lshl_add_u64 v[114:115], v[114:115], 1, s[66:67]
	v_lshl_add_u64 v[98:99], v[98:99], 1, s[66:67]
	v_lshl_add_u32 v25, v189, 3, 0
	v_lshl_add_u64 v[82:83], v[82:83], 1, s[66:67]
	s_waitcnt lgkmcnt(0)
	v_sub_f32_e32 v23, v157, v184
	v_sub_f32_e32 v22, v156, v184
	v_sub_f32_e32 v147, v155, v184
	v_sub_f32_e32 v146, v154, v184
	v_pk_mul_f32 v[146:147], v[184:185], v[146:147] op_sel:[1,0]
	v_pk_mul_f32 v[22:23], v[184:185], v[22:23] op_sel:[1,0]
	v_sub_f32_e32 v133, v133, v184
	v_sub_f32_e32 v132, v132, v184
	v_sub_f32_e32 v131, v131, v184
	v_sub_f32_e32 v130, v130, v184
	v_pk_mul_f32 v[130:131], v[184:185], v[130:131] op_sel:[1,0]
	v_pk_mul_f32 v[132:133], v[184:185], v[132:133] op_sel:[1,0]
	v_sub_f32_e32 v121, v121, v186
	v_sub_f32_e32 v120, v120, v186
	v_sub_f32_e32 v117, v117, v186
	v_sub_f32_e32 v116, v116, v186
	v_pk_mul_f32 v[116:117], v[186:187], v[116:117] op_sel:[1,0]
	v_pk_mul_f32 v[120:121], v[186:187], v[120:121] op_sel:[1,0]
	v_sub_f32_e32 v119, v119, v186
	v_sub_f32_e32 v118, v118, v186
	v_pk_mul_f32 v[118:119], v[186:187], v[118:119] op_sel:[1,0]
	s_mov_b32 s26, 32
	s_mov_b64 s[8:9], 0
	s_and_b64 vcc, exec, s[24:25]
	v_pk_fma_f32 v[22:23], v[28:29], v[22:23], v[32:33]
	v_pk_fma_f32 v[26:27], v[26:27], v[146:147], v[30:31]
	v_lshl_add_u64 v[146:147], v[150:151], 1, s[66:67]
	v_cvt_pk_bf16_f32 v26, v26, v27
	v_cvt_pk_bf16_f32 v27, v22, v23
	global_store_dwordx2 v[152:153], v[26:27], off
	v_mov_b64_e32 v[26:27], v[228:229]
	v_mov_b64_e32 v[28:29], v[230:231]
	s_nop 0
	v_mov_b64_e32 v[30:31], v[244:245]
	v_mov_b64_e32 v[32:33], v[246:247]
	v_lshlrev_b64 v[22:23], 1, v[148:149]
	v_lshl_add_u64 v[146:147], v[146:147], 0, v[22:23]
	v_lshl_add_u64 v[114:115], v[114:115], 0, v[22:23]
	v_lshl_add_u64 v[98:99], v[98:99], 0, v[22:23]
	v_lshl_add_u64 v[82:83], v[82:83], 0, v[22:23]
	v_pk_fma_f32 v[28:29], v[132:133], v[28:29], v[32:33]
	v_pk_fma_f32 v[26:27], v[130:131], v[26:27], v[30:31]
	v_sub_f32_e32 v131, v141, v184
	v_cvt_pk_bf16_f32 v26, v26, v27
	v_cvt_pk_bf16_f32 v27, v28, v29
	global_store_dwordx2 v[146:147], v[26:27], off offset:32
	v_mov_b64_e32 v[26:27], v[232:233]
	v_mov_b64_e32 v[28:29], v[234:235]
	s_nop 0
	v_mov_b64_e32 v[30:31], v[248:249]
	v_mov_b64_e32 v[32:33], v[250:251]
	v_sub_f32_e32 v130, v140, v184
	v_sub_f32_e32 v133, v137, v184
	v_sub_f32_e32 v132, v136, v184
	v_pk_mul_f32 v[132:133], v[184:185], v[132:133] op_sel:[1,0]
	v_pk_mul_f32 v[130:131], v[184:185], v[130:131] op_sel:[1,0]
	v_pk_fma_f32 v[26:27], v[132:133], v[26:27], v[30:31]
	v_pk_fma_f32 v[28:29], v[130:131], v[28:29], v[32:33]
	v_cvt_pk_bf16_f32 v26, v26, v27
	v_cvt_pk_bf16_f32 v27, v28, v29
	global_store_dwordx2 v[146:147], v[26:27], off offset:256
	v_mov_b64_e32 v[26:27], v[236:237]
	v_mov_b64_e32 v[28:29], v[238:239]
	s_nop 0
	v_mov_b64_e32 v[30:31], v[194:195]
	v_mov_b64_e32 v[32:33], v[196:197]
	v_sub_f32_e32 v131, v145, v184
	v_sub_f32_e32 v130, v144, v184
	v_sub_f32_e32 v133, v139, v184
	v_sub_f32_e32 v132, v138, v184
	v_pk_mul_f32 v[132:133], v[184:185], v[132:133] op_sel:[1,0]
	v_pk_mul_f32 v[130:131], v[184:185], v[130:131] op_sel:[1,0]
	v_pk_fma_f32 v[26:27], v[132:133], v[26:27], v[30:31]
	v_pk_fma_f32 v[28:29], v[130:131], v[28:29], v[32:33]
	v_cvt_pk_bf16_f32 v26, v26, v27
	v_cvt_pk_bf16_f32 v27, v28, v29
	global_store_dwordx2 v[146:147], v[26:27], off offset:288
	v_mov_b64_e32 v[26:27], v[224:225]
	v_mov_b64_e32 v[28:29], v[226:227]
	s_nop 0
	v_mov_b64_e32 v[30:31], v[240:241]
	v_mov_b64_e32 v[32:33], v[242:243]
	v_sub_f32_e32 v131, v161, v186
	v_sub_f32_e32 v130, v160, v186
	v_sub_f32_e32 v133, v159, v186
	v_sub_f32_e32 v132, v158, v186
	v_pk_mul_f32 v[132:133], v[186:187], v[132:133] op_sel:[1,0]
	v_pk_mul_f32 v[130:131], v[186:187], v[130:131] op_sel:[1,0]
	v_pk_fma_f32 v[26:27], v[26:27], v[132:133], v[30:31]
	v_pk_fma_f32 v[28:29], v[28:29], v[130:131], v[32:33]
	v_cvt_pk_bf16_f32 v26, v26, v27
	v_cvt_pk_bf16_f32 v27, v28, v29
	global_store_dwordx2 v[142:143], v[26:27], off
	v_mov_b64_e32 v[26:27], v[228:229]
	v_mov_b64_e32 v[28:29], v[230:231]
	s_nop 0
	v_mov_b64_e32 v[30:31], v[244:245]
	v_mov_b64_e32 v[32:33], v[246:247]
	v_lshl_add_u64 v[130:131], v[134:135], 1, s[66:67]
	v_lshl_add_u64 v[130:131], v[130:131], 0, v[22:23]
	v_pk_fma_f32 v[28:29], v[120:121], v[28:29], v[32:33]
	v_pk_fma_f32 v[26:27], v[116:117], v[26:27], v[30:31]
	v_sub_f32_e32 v117, v125, v186
	v_cvt_pk_bf16_f32 v26, v26, v27
	v_cvt_pk_bf16_f32 v27, v28, v29
	global_store_dwordx2 v[130:131], v[26:27], off offset:32
	v_mov_b64_e32 v[26:27], v[232:233]
	v_mov_b64_e32 v[28:29], v[234:235]
	s_nop 0
	v_mov_b64_e32 v[30:31], v[248:249]
	v_mov_b64_e32 v[32:33], v[250:251]
	v_sub_f32_e32 v116, v124, v186
	v_pk_mul_f32 v[116:117], v[186:187], v[116:117] op_sel:[1,0]
	v_pk_fma_f32 v[26:27], v[118:119], v[26:27], v[30:31]
	v_pk_fma_f32 v[28:29], v[116:117], v[28:29], v[32:33]
	v_cvt_pk_bf16_f32 v26, v26, v27
	v_cvt_pk_bf16_f32 v27, v28, v29
	global_store_dwordx2 v[130:131], v[26:27], off offset:256
	v_mov_b64_e32 v[26:27], v[236:237]
	v_mov_b64_e32 v[28:29], v[238:239]
	s_nop 0
	v_mov_b64_e32 v[30:31], v[194:195]
	v_mov_b64_e32 v[32:33], v[196:197]
	v_sub_f32_e32 v117, v129, v186
	v_sub_f32_e32 v116, v128, v186
	v_sub_f32_e32 v119, v123, v186
	v_sub_f32_e32 v118, v122, v186
	v_pk_mul_f32 v[118:119], v[186:187], v[118:119] op_sel:[1,0]
	v_pk_mul_f32 v[116:117], v[186:187], v[116:117] op_sel:[1,0]
	v_pk_fma_f32 v[26:27], v[118:119], v[26:27], v[30:31]
	v_pk_fma_f32 v[28:29], v[116:117], v[28:29], v[32:33]
	v_cvt_pk_bf16_f32 v26, v26, v27
	v_cvt_pk_bf16_f32 v27, v28, v29
	global_store_dwordx2 v[130:131], v[26:27], off offset:288
	v_mov_b64_e32 v[26:27], v[224:225]
	v_mov_b64_e32 v[28:29], v[226:227]
	s_nop 0
	v_mov_b64_e32 v[30:31], v[240:241]
	v_mov_b64_e32 v[32:33], v[242:243]
	ds_read2_b64 v[116:119], v24 offset0:32 offset1:48
	s_waitcnt lgkmcnt(0)
; template <int EPI>
; DI void gemm_unit(const GemmP& g, int pm, int pn) {
;     ...
; #pragma unroll
;     for (int ai = 0; ai < 2; ++ai)
; #pragma unroll
;       for (int m = 0; m < 4; ++m) {
;         const int rl = ai * 128 + wr * 64 + m * 16 + fr;
;         const float mean = mr[rl * 2], rs = mr[rl * 2 + 1];
;         const int row = row0 + ai * 128 + m * 16;
; #pragma unroll
;         for (int bj = 0; bj < 2; ++bj)
; #pragma unroll
;           for (int n = 0; n < 2; ++n) {
;             const int col = colb + bj * 128 + n * 16;
;             const f32x4 gg = *(const f32x4*)(g.ln_g + col), bb = *(const f32x4*)(g.ln_b + col);
;             const f32x4 o = (acc[ai][bj][m][n] - mean) * rs * gg + bb;
;             const size_t idx = (size_t)row * 2048 + col;
;             if (g.outf) *(f32x4*)(g.outf + idx) = o;
;             uint2 ob; ob.x = pk2(o[0], o[1]); ob.y = pk2(o[2], o[3]);
;             *(uint2*)(g.outb + idx) = ob;
;           }
;       }
	v_sub_f32_e32 v121, v167, v116
	v_sub_f32_e32 v120, v166, v116
	v_sub_f32_e32 v123, v165, v116
	v_sub_f32_e32 v122, v164, v116
	v_pk_mul_f32 v[122:123], v[116:117], v[122:123] op_sel:[1,0]
	v_pk_mul_f32 v[120:121], v[116:117], v[120:121] op_sel:[1,0]
	v_sub_f32_e32 v105, v105, v116
	v_sub_f32_e32 v104, v104, v116
	v_sub_f32_e32 v101, v101, v116
	v_sub_f32_e32 v100, v100, v116
	v_pk_mul_f32 v[100:101], v[116:117], v[100:101] op_sel:[1,0]
	v_pk_mul_f32 v[104:105], v[116:117], v[104:105] op_sel:[1,0]
	v_sub_f32_e32 v103, v103, v116
	v_sub_f32_e32 v102, v102, v116
	v_pk_mul_f32 v[102:103], v[116:117], v[102:103] op_sel:[1,0]
	v_sub_f32_e32 v89, v89, v118
	v_sub_f32_e32 v88, v88, v118
	v_sub_f32_e32 v85, v85, v118
	v_sub_f32_e32 v84, v84, v118
	v_pk_mul_f32 v[84:85], v[118:119], v[84:85] op_sel:[1,0]
	v_pk_mul_f32 v[88:89], v[118:119], v[88:89] op_sel:[1,0]
	v_sub_f32_e32 v87, v87, v118
	v_sub_f32_e32 v86, v86, v118
	v_pk_mul_f32 v[86:87], v[118:119], v[86:87] op_sel:[1,0]
	v_pk_fma_f32 v[28:29], v[28:29], v[120:121], v[32:33]
	v_pk_fma_f32 v[26:27], v[26:27], v[122:123], v[30:31]
	s_nop 0
	v_cvt_pk_bf16_f32 v26, v26, v27
	v_cvt_pk_bf16_f32 v27, v28, v29
	global_store_dwordx2 v[126:127], v[26:27], off
	v_mov_b64_e32 v[26:27], v[228:229]
	v_mov_b64_e32 v[28:29], v[230:231]
	s_nop 0
	v_mov_b64_e32 v[30:31], v[244:245]
	v_mov_b64_e32 v[32:33], v[246:247]
	v_pk_fma_f32 v[28:29], v[104:105], v[28:29], v[32:33]
	v_pk_fma_f32 v[26:27], v[100:101], v[26:27], v[30:31]
	v_sub_f32_e32 v101, v109, v116
	v_cvt_pk_bf16_f32 v26, v26, v27
	v_cvt_pk_bf16_f32 v27, v28, v29
	global_store_dwordx2 v[114:115], v[26:27], off offset:32
	v_mov_b64_e32 v[26:27], v[232:233]
	v_mov_b64_e32 v[28:29], v[234:235]
	s_nop 0
	v_mov_b64_e32 v[30:31], v[248:249]
	v_mov_b64_e32 v[32:33], v[250:251]
	v_sub_f32_e32 v100, v108, v116
	v_pk_mul_f32 v[100:101], v[116:117], v[100:101] op_sel:[1,0]
	v_pk_fma_f32 v[26:27], v[102:103], v[26:27], v[30:31]
	v_pk_fma_f32 v[28:29], v[100:101], v[28:29], v[32:33]
	v_cvt_pk_bf16_f32 v26, v26, v27
	v_cvt_pk_bf16_f32 v27, v28, v29
	global_store_dwordx2 v[114:115], v[26:27], off offset:256
	v_mov_b64_e32 v[26:27], v[236:237]
	v_mov_b64_e32 v[28:29], v[238:239]
	s_nop 0
	v_mov_b64_e32 v[30:31], v[194:195]
	v_mov_b64_e32 v[32:33], v[196:197]
	v_sub_f32_e32 v101, v113, v116
	v_sub_f32_e32 v100, v112, v116
	v_sub_f32_e32 v103, v107, v116
	v_sub_f32_e32 v102, v106, v116
	v_pk_mul_f32 v[102:103], v[116:117], v[102:103] op_sel:[1,0]
	v_pk_mul_f32 v[100:101], v[116:117], v[100:101] op_sel:[1,0]
	v_pk_fma_f32 v[26:27], v[102:103], v[26:27], v[30:31]
	v_pk_fma_f32 v[28:29], v[100:101], v[28:29], v[32:33]
	v_cvt_pk_bf16_f32 v26, v26, v27
	v_cvt_pk_bf16_f32 v27, v28, v29
	global_store_dwordx2 v[114:115], v[26:27], off offset:288
	v_mov_b64_e32 v[26:27], v[224:225]
	v_mov_b64_e32 v[28:29], v[226:227]
	s_nop 0
	v_mov_b64_e32 v[30:31], v[240:241]
	v_mov_b64_e32 v[32:33], v[242:243]
	v_sub_f32_e32 v101, v171, v118
	v_sub_f32_e32 v100, v170, v118
	v_sub_f32_e32 v103, v169, v118
	v_sub_f32_e32 v102, v168, v118
	v_pk_mul_f32 v[102:103], v[118:119], v[102:103] op_sel:[1,0]
	v_pk_mul_f32 v[100:101], v[118:119], v[100:101] op_sel:[1,0]
	v_pk_fma_f32 v[26:27], v[26:27], v[102:103], v[30:31]
	v_pk_fma_f32 v[28:29], v[28:29], v[100:101], v[32:33]
	v_cvt_pk_bf16_f32 v26, v26, v27
	v_cvt_pk_bf16_f32 v27, v28, v29
	global_store_dwordx2 v[110:111], v[26:27], off
	v_mov_b64_e32 v[26:27], v[228:229]
	v_mov_b64_e32 v[28:29], v[230:231]
	s_nop 0
	v_mov_b64_e32 v[30:31], v[244:245]
	v_mov_b64_e32 v[32:33], v[246:247]
	v_pk_fma_f32 v[28:29], v[88:89], v[28:29], v[32:33]
	v_pk_fma_f32 v[26:27], v[84:85], v[26:27], v[30:31]
	v_sub_f32_e32 v85, v93, v118
	v_cvt_pk_bf16_f32 v26, v26, v27
	v_cvt_pk_bf16_f32 v27, v28, v29
	global_store_dwordx2 v[98:99], v[26:27], off offset:32
	v_mov_b64_e32 v[26:27], v[232:233]
	v_mov_b64_e32 v[28:29], v[234:235]
	s_nop 0
	v_mov_b64_e32 v[30:31], v[248:249]
	v_mov_b64_e32 v[32:33], v[250:251]
	v_sub_f32_e32 v84, v92, v118
	v_pk_mul_f32 v[84:85], v[118:119], v[84:85] op_sel:[1,0]
	v_pk_fma_f32 v[26:27], v[86:87], v[26:27], v[30:31]
	v_pk_fma_f32 v[28:29], v[84:85], v[28:29], v[32:33]
	v_cvt_pk_bf16_f32 v26, v26, v27
	v_cvt_pk_bf16_f32 v27, v28, v29
	global_store_dwordx2 v[98:99], v[26:27], off offset:256
	v_mov_b64_e32 v[26:27], v[236:237]
	v_mov_b64_e32 v[28:29], v[238:239]
	s_nop 0
	v_mov_b64_e32 v[30:31], v[194:195]
	v_mov_b64_e32 v[32:33], v[196:197]
	v_sub_f32_e32 v85, v97, v118
	v_sub_f32_e32 v84, v96, v118
	v_sub_f32_e32 v87, v91, v118
	v_sub_f32_e32 v86, v90, v118
	v_pk_mul_f32 v[86:87], v[118:119], v[86:87] op_sel:[1,0]
	v_pk_mul_f32 v[84:85], v[118:119], v[84:85] op_sel:[1,0]
	v_pk_fma_f32 v[26:27], v[86:87], v[26:27], v[30:31]
	v_pk_fma_f32 v[28:29], v[84:85], v[28:29], v[32:33]
	v_cvt_pk_bf16_f32 v26, v26, v27
	v_cvt_pk_bf16_f32 v27, v28, v29
	global_store_dwordx2 v[98:99], v[26:27], off offset:288
	v_mov_b64_e32 v[26:27], v[224:225]
	v_mov_b64_e32 v[28:29], v[226:227]
	s_nop 0
	v_mov_b64_e32 v[30:31], v[240:241]
	v_mov_b64_e32 v[32:33], v[242:243]
	ds_read_b64 v[84:85], v25 offset:8192
	s_waitcnt lgkmcnt(0)
; template <int EPI>
; DI void gemm_unit(const GemmP& g, int pm, int pn) {
;     ...
; #pragma unroll
;     for (int ai = 0; ai < 2; ++ai)
; #pragma unroll
;       for (int m = 0; m < 4; ++m) {
;         const int rl = ai * 128 + wr * 64 + m * 16 + fr;
;         const float mean = mr[rl * 2], rs = mr[rl * 2 + 1];
;         const int row = row0 + ai * 128 + m * 16;
; #pragma unroll
;         for (int bj = 0; bj < 2; ++bj)
; #pragma unroll
;           for (int n = 0; n < 2; ++n) {
;             const int col = colb + bj * 128 + n * 16;
;             const f32x4 gg = *(const f32x4*)(g.ln_g + col), bb = *(const f32x4*)(g.ln_b + col);
;             const f32x4 o = (acc[ai][bj][m][n] - mean) * rs * gg + bb;
;             const size_t idx = (size_t)row * 2048 + col;
;             if (g.outf) *(f32x4*)(g.outf + idx) = o;
;             uint2 ob; ob.x = pk2(o[0], o[1]); ob.y = pk2(o[2], o[3]);
;             *(uint2*)(g.outb + idx) = ob;
;           }
;       }
	v_sub_f32_e32 v87, v175, v84
	v_sub_f32_e32 v86, v174, v84
	v_sub_f32_e32 v89, v173, v84
	v_sub_f32_e32 v88, v172, v84
	v_pk_mul_f32 v[88:89], v[84:85], v[88:89] op_sel:[1,0]
	v_pk_mul_f32 v[86:87], v[84:85], v[86:87] op_sel:[1,0]
	v_sub_f32_e32 v73, v73, v84
	v_sub_f32_e32 v72, v72, v84
	v_sub_f32_e32 v69, v69, v84
	v_sub_f32_e32 v68, v68, v84
	v_pk_mul_f32 v[68:69], v[84:85], v[68:69] op_sel:[1,0]
	v_pk_mul_f32 v[72:73], v[84:85], v[72:73] op_sel:[1,0]
	v_sub_f32_e32 v71, v71, v84
	v_sub_f32_e32 v70, v70, v84
	v_pk_mul_f32 v[70:71], v[84:85], v[70:71] op_sel:[1,0]
	v_pk_fma_f32 v[28:29], v[28:29], v[86:87], v[32:33]
	v_pk_fma_f32 v[26:27], v[26:27], v[88:89], v[30:31]
	s_nop 0
	v_cvt_pk_bf16_f32 v26, v26, v27
	v_cvt_pk_bf16_f32 v27, v28, v29
	global_store_dwordx2 v[94:95], v[26:27], off
	v_mov_b64_e32 v[26:27], v[228:229]
	v_mov_b64_e32 v[28:29], v[230:231]
	s_nop 0
	v_mov_b64_e32 v[30:31], v[244:245]
	v_mov_b64_e32 v[32:33], v[246:247]
	v_pk_fma_f32 v[28:29], v[72:73], v[28:29], v[32:33]
	v_pk_fma_f32 v[26:27], v[68:69], v[26:27], v[30:31]
	v_sub_f32_e32 v69, v77, v84
	v_cvt_pk_bf16_f32 v26, v26, v27
	v_cvt_pk_bf16_f32 v27, v28, v29
	global_store_dwordx2 v[82:83], v[26:27], off offset:32
	v_mov_b64_e32 v[26:27], v[232:233]
	v_mov_b64_e32 v[28:29], v[234:235]
	s_nop 0
	v_mov_b64_e32 v[30:31], v[248:249]
	v_mov_b64_e32 v[32:33], v[250:251]
	v_sub_f32_e32 v68, v76, v84
	v_pk_mul_f32 v[68:69], v[84:85], v[68:69] op_sel:[1,0]
	v_pk_fma_f32 v[26:27], v[70:71], v[26:27], v[30:31]
	v_pk_fma_f32 v[28:29], v[68:69], v[28:29], v[32:33]
	v_cvt_pk_bf16_f32 v26, v26, v27
	v_cvt_pk_bf16_f32 v27, v28, v29
	global_store_dwordx2 v[82:83], v[26:27], off offset:256
	v_mov_b64_e32 v[26:27], v[236:237]
	v_mov_b64_e32 v[28:29], v[238:239]
	s_nop 0
	v_mov_b64_e32 v[30:31], v[194:195]
	v_mov_b64_e32 v[32:33], v[196:197]
	v_sub_f32_e32 v69, v81, v84
	v_sub_f32_e32 v68, v80, v84
	v_sub_f32_e32 v71, v75, v84
	v_sub_f32_e32 v70, v74, v84
	v_pk_mul_f32 v[70:71], v[84:85], v[70:71] op_sel:[1,0]
	v_pk_mul_f32 v[68:69], v[84:85], v[68:69] op_sel:[1,0]
	v_pk_fma_f32 v[26:27], v[70:71], v[26:27], v[30:31]
	v_pk_fma_f32 v[28:29], v[68:69], v[28:29], v[32:33]
	v_cvt_pk_bf16_f32 v26, v26, v27
	v_cvt_pk_bf16_f32 v27, v28, v29
	global_store_dwordx2 v[82:83], v[26:27], off offset:288
	v_mov_b64_e32 v[26:27], v[224:225]
	v_mov_b64_e32 v[28:29], v[226:227]
	s_nop 0
	v_mov_b64_e32 v[30:31], v[240:241]
	v_mov_b64_e32 v[32:33], v[242:243]
	ds_read2_b64 v[68:71], v24 offset0:144 offset1:160
	s_waitcnt lgkmcnt(0)
	v_sub_f32_e32 v25, v179, v68
	v_sub_f32_e32 v24, v178, v68
	v_sub_f32_e32 v73, v177, v68
	v_sub_f32_e32 v72, v176, v68
	v_pk_mul_f32 v[72:73], v[68:69], v[72:73] op_sel:[1,0]
	v_pk_mul_f32 v[24:25], v[68:69], v[24:25] op_sel:[1,0]
	v_sub_f32_e32 v57, v57, v68
	v_sub_f32_e32 v56, v56, v68
	v_sub_f32_e32 v53, v53, v68
	v_sub_f32_e32 v52, v52, v68
	v_pk_mul_f32 v[52:53], v[68:69], v[52:53] op_sel:[1,0]
	v_pk_mul_f32 v[56:57], v[68:69], v[56:57] op_sel:[1,0]
	v_sub_f32_e32 v55, v55, v68
	v_sub_f32_e32 v54, v54, v68
	v_pk_mul_f32 v[54:55], v[68:69], v[54:55] op_sel:[1,0]
	v_sub_f32_e32 v41, v41, v70
	v_sub_f32_e32 v40, v40, v70
	v_sub_f32_e32 v37, v37, v70
	v_sub_f32_e32 v36, v36, v70
	v_pk_mul_f32 v[36:37], v[70:71], v[36:37] op_sel:[1,0]
	v_pk_mul_f32 v[40:41], v[70:71], v[40:41] op_sel:[1,0]
	v_sub_f32_e32 v39, v39, v70
	v_sub_f32_e32 v38, v38, v70
	v_pk_mul_f32 v[38:39], v[70:71], v[38:39] op_sel:[1,0]
	v_pk_fma_f32 v[24:25], v[28:29], v[24:25], v[32:33]
	v_pk_fma_f32 v[26:27], v[26:27], v[72:73], v[30:31]
	v_lshl_add_u64 v[32:33], v[66:67], 1, s[66:67]
	v_cvt_pk_bf16_f32 v26, v26, v27
	v_cvt_pk_bf16_f32 v27, v24, v25
	global_store_dwordx2 v[78:79], v[26:27], off
	v_mov_b64_e32 v[24:25], v[228:229]
	v_mov_b64_e32 v[26:27], v[230:231]
	s_nop 0
	v_mov_b64_e32 v[28:29], v[244:245]
	v_mov_b64_e32 v[30:31], v[246:247]
	v_lshl_add_u64 v[32:33], v[32:33], 0, v[22:23]
	v_pk_fma_f32 v[26:27], v[56:57], v[26:27], v[30:31]
	v_pk_fma_f32 v[24:25], v[52:53], v[24:25], v[28:29]
	v_sub_f32_e32 v53, v61, v68
	v_cvt_pk_bf16_f32 v24, v24, v25
	v_cvt_pk_bf16_f32 v25, v26, v27
	global_store_dwordx2 v[32:33], v[24:25], off offset:32
	v_mov_b64_e32 v[24:25], v[232:233]
	v_mov_b64_e32 v[26:27], v[234:235]
	s_nop 0
	v_mov_b64_e32 v[28:29], v[248:249]
	v_mov_b64_e32 v[30:31], v[250:251]
	v_sub_f32_e32 v52, v60, v68
	v_pk_mul_f32 v[52:53], v[68:69], v[52:53] op_sel:[1,0]
	v_pk_fma_f32 v[24:25], v[54:55], v[24:25], v[28:29]
	v_pk_fma_f32 v[26:27], v[52:53], v[26:27], v[30:31]
	v_cvt_pk_bf16_f32 v24, v24, v25
	v_cvt_pk_bf16_f32 v25, v26, v27
	global_store_dwordx2 v[32:33], v[24:25], off offset:256
	v_mov_b64_e32 v[24:25], v[236:237]
	v_mov_b64_e32 v[26:27], v[238:239]
	s_nop 0
	v_mov_b64_e32 v[28:29], v[194:195]
	v_mov_b64_e32 v[30:31], v[196:197]
	v_sub_f32_e32 v53, v65, v68
	v_sub_f32_e32 v52, v64, v68
	v_sub_f32_e32 v55, v59, v68
	v_sub_f32_e32 v54, v58, v68
	v_pk_mul_f32 v[54:55], v[68:69], v[54:55] op_sel:[1,0]
	v_pk_mul_f32 v[52:53], v[68:69], v[52:53] op_sel:[1,0]
; template <int EPI>
; DI void gemm_unit(const GemmP& g, int pm, int pn) {
;     ...
; #pragma unroll
;     for (int ai = 0; ai < 2; ++ai)
; #pragma unroll
;       for (int m = 0; m < 4; ++m) {
;         const int rl = ai * 128 + wr * 64 + m * 16 + fr;
;         const float mean = mr[rl * 2], rs = mr[rl * 2 + 1];
;         const int row = row0 + ai * 128 + m * 16;
; #pragma unroll
;         for (int bj = 0; bj < 2; ++bj)
; #pragma unroll
;           for (int n = 0; n < 2; ++n) {
;             const int col = colb + bj * 128 + n * 16;
;             const f32x4 gg = *(const f32x4*)(g.ln_g + col), bb = *(const f32x4*)(g.ln_b + col);
;             const f32x4 o = (acc[ai][bj][m][n] - mean) * rs * gg + bb;
;             const size_t idx = (size_t)row * 2048 + col;
;             if (g.outf) *(f32x4*)(g.outf + idx) = o;
;             uint2 ob; ob.x = pk2(o[0], o[1]); ob.y = pk2(o[2], o[3]);
;             *(uint2*)(g.outb + idx) = ob;
;           }
;       }
;     __syncthreads();
	v_pk_fma_f32 v[24:25], v[54:55], v[24:25], v[28:29]
	v_pk_fma_f32 v[26:27], v[52:53], v[26:27], v[30:31]
	v_cvt_pk_bf16_f32 v24, v24, v25
	v_cvt_pk_bf16_f32 v25, v26, v27
	global_store_dwordx2 v[32:33], v[24:25], off offset:288
	v_mov_b64_e32 v[24:25], v[224:225]
	v_mov_b64_e32 v[26:27], v[226:227]
	s_nop 0
	v_mov_b64_e32 v[28:29], v[240:241]
	v_mov_b64_e32 v[30:31], v[242:243]
	v_sub_f32_e32 v33, v183, v70
	v_sub_f32_e32 v32, v182, v70
	v_sub_f32_e32 v53, v181, v70
	v_sub_f32_e32 v52, v180, v70
	v_pk_mul_f32 v[52:53], v[70:71], v[52:53] op_sel:[1,0]
	v_pk_mul_f32 v[32:33], v[70:71], v[32:33] op_sel:[1,0]
	v_pk_fma_f32 v[24:25], v[24:25], v[52:53], v[28:29]
	v_pk_fma_f32 v[26:27], v[26:27], v[32:33], v[30:31]
	v_cvt_pk_bf16_f32 v24, v24, v25
	v_cvt_pk_bf16_f32 v25, v26, v27
	global_store_dwordx2 v[62:63], v[24:25], off
	v_mov_b64_e32 v[24:25], v[228:229]
	v_mov_b64_e32 v[26:27], v[230:231]
	s_nop 0
	v_mov_b64_e32 v[28:29], v[244:245]
	v_mov_b64_e32 v[30:31], v[246:247]
	v_lshl_add_u64 v[32:33], v[50:51], 1, s[66:67]
	v_lshl_add_u64 v[32:33], v[32:33], 0, v[22:23]
	v_pk_fma_f32 v[26:27], v[40:41], v[26:27], v[30:31]
	v_pk_fma_f32 v[24:25], v[36:37], v[24:25], v[28:29]
	v_sub_f32_e32 v37, v45, v70
	v_cvt_pk_bf16_f32 v24, v24, v25
	v_cvt_pk_bf16_f32 v25, v26, v27
	global_store_dwordx2 v[32:33], v[24:25], off offset:32
	v_mov_b64_e32 v[24:25], v[232:233]
	v_mov_b64_e32 v[26:27], v[234:235]
	s_nop 0
	v_mov_b64_e32 v[28:29], v[248:249]
	v_mov_b64_e32 v[30:31], v[250:251]
	v_sub_f32_e32 v36, v44, v70
	v_pk_mul_f32 v[36:37], v[70:71], v[36:37] op_sel:[1,0]
	v_pk_fma_f32 v[24:25], v[38:39], v[24:25], v[28:29]
	v_pk_fma_f32 v[26:27], v[36:37], v[26:27], v[30:31]
	v_cvt_pk_bf16_f32 v24, v24, v25
	v_cvt_pk_bf16_f32 v25, v26, v27
	global_store_dwordx2 v[32:33], v[24:25], off offset:256
	v_mov_b64_e32 v[24:25], v[236:237]
	v_mov_b64_e32 v[26:27], v[238:239]
	s_nop 0
	v_mov_b64_e32 v[28:29], v[194:195]
	v_mov_b64_e32 v[30:31], v[196:197]
	v_sub_f32_e32 v37, v49, v70
	v_sub_f32_e32 v36, v48, v70
	v_sub_f32_e32 v39, v43, v70
	v_sub_f32_e32 v38, v42, v70
	v_pk_mul_f32 v[38:39], v[70:71], v[38:39] op_sel:[1,0]
	v_pk_mul_f32 v[36:37], v[70:71], v[36:37] op_sel:[1,0]
	v_pk_fma_f32 v[24:25], v[38:39], v[24:25], v[28:29]
	v_pk_fma_f32 v[26:27], v[36:37], v[26:27], v[30:31]
	v_cvt_pk_bf16_f32 v24, v24, v25
	v_cvt_pk_bf16_f32 v25, v26, v27
	global_store_dwordx2 v[32:33], v[24:25], off offset:288
	v_mov_b64_e32 v[24:25], v[224:225]
	v_mov_b64_e32 v[26:27], v[226:227]
	s_nop 0
	v_mov_b64_e32 v[28:29], v[240:241]
	v_mov_b64_e32 v[30:31], v[242:243]
	ds_read_b64 v[32:33], v0 offset:9600
	s_waitcnt lgkmcnt(0)
	v_sub_f32_e32 v17, v17, v32
	v_sub_f32_e32 v16, v16, v32
	v_sub_f32_e32 v15, v15, v32
	v_sub_f32_e32 v14, v14, v32
	v_pk_mul_f32 v[14:15], v[32:33], v[14:15] op_sel:[1,0]
	v_pk_mul_f32 v[16:17], v[32:33], v[16:17] op_sel:[1,0]
	v_sub_f32_e32 v13, v13, v32
	v_sub_f32_e32 v12, v12, v32
	v_sub_f32_e32 v11, v11, v32
	v_sub_f32_e32 v10, v10, v32
	v_pk_mul_f32 v[10:11], v[32:33], v[10:11] op_sel:[1,0]
	v_pk_mul_f32 v[12:13], v[32:33], v[12:13] op_sel:[1,0]
	v_sub_f32_e32 v9, v9, v32
	v_sub_f32_e32 v8, v8, v32
	v_sub_f32_e32 v7, v7, v32
	v_sub_f32_e32 v6, v6, v32
	v_pk_mul_f32 v[6:7], v[32:33], v[6:7] op_sel:[1,0]
	v_pk_mul_f32 v[8:9], v[32:33], v[8:9] op_sel:[1,0]
	v_sub_f32_e32 v5, v5, v32
	v_sub_f32_e32 v4, v4, v32
	v_sub_f32_e32 v3, v3, v32
	v_sub_f32_e32 v2, v2, v32
	v_pk_mul_f32 v[2:3], v[32:33], v[2:3] op_sel:[1,0]
	v_pk_mul_f32 v[4:5], v[32:33], v[4:5] op_sel:[1,0]
	v_pk_fma_f32 v[16:17], v[26:27], v[16:17], v[30:31]
	v_pk_fma_f32 v[14:15], v[24:25], v[14:15], v[28:29]
	v_lshl_add_u64 v[28:29], v[34:35], 1, s[66:67]
	v_cvt_pk_bf16_f32 v14, v14, v15
	v_cvt_pk_bf16_f32 v15, v16, v17
	global_store_dwordx2 v[46:47], v[14:15], off
	v_mov_b64_e32 v[14:15], v[228:229]
	v_mov_b64_e32 v[16:17], v[230:231]
	s_nop 0
	v_mov_b64_e32 v[24:25], v[244:245]
	v_mov_b64_e32 v[26:27], v[246:247]
	v_lshl_add_u64 v[22:23], v[28:29], 0, v[22:23]
	v_pk_fma_f32 v[12:13], v[12:13], v[16:17], v[26:27]
	v_pk_fma_f32 v[10:11], v[10:11], v[14:15], v[24:25]
	s_nop 0
	v_cvt_pk_bf16_f32 v10, v10, v11
	v_cvt_pk_bf16_f32 v11, v12, v13
	global_store_dwordx2 v[22:23], v[10:11], off offset:32
	v_mov_b64_e32 v[10:11], v[232:233]
	v_mov_b64_e32 v[12:13], v[234:235]
	s_nop 0
	v_mov_b64_e32 v[14:15], v[248:249]
	v_mov_b64_e32 v[16:17], v[250:251]
	v_pk_fma_f32 v[8:9], v[8:9], v[12:13], v[16:17]
	v_pk_fma_f32 v[6:7], v[6:7], v[10:11], v[14:15]
	s_nop 0
	v_cvt_pk_bf16_f32 v6, v6, v7
	v_cvt_pk_bf16_f32 v7, v8, v9
	global_store_dwordx2 v[22:23], v[6:7], off offset:256
	v_mov_b64_e32 v[6:7], v[236:237]
	v_mov_b64_e32 v[8:9], v[238:239]
	s_nop 0
	v_mov_b64_e32 v[10:11], v[194:195]
	v_mov_b64_e32 v[12:13], v[196:197]
	v_pk_fma_f32 v[4:5], v[4:5], v[8:9], v[12:13]
	v_pk_fma_f32 v[2:3], v[2:3], v[6:7], v[10:11]
	s_nop 0
	v_cvt_pk_bf16_f32 v2, v2, v3
	v_cvt_pk_bf16_f32 v3, v4, v5
	global_store_dwordx2 v[22:23], v[2:3], off offset:288
	s_barrier
	s_cbranch_vccnz .LBB0_462
